# LN3 finalize: the first three wig columns' LDS reads issued at the start of each row block, under the LayerNorm math, instead of at the finalize head
# baseline (speedup 1.0000x reference)
; __device__ __forceinline__ float wave_sum(float v) { return rdlane(dpp_sum63(v), 63); }
; __device__ __forceinline__ void row_ln(f32x4 (&v)[4], const float* g, const float* b, int lane) {
;     float s = 0.f;
; #pragma unroll
;     for (int j = 0; j < 4; ++j) s += (v[j][0] + v[j][1]) + (v[j][2] + v[j][3]);
;     const float mean = wave_sum(s) * (1.f / D); float s2 = 0.f;
; #pragma unroll
;     for (int j = 0; j < 4; ++j) { v[j] = v[j] - mean; s2 += (v[j][0] * v[j][0] + v[j][1] * v[j][1]) + (v[j][2] * v[j][2] + v[j][3] * v[j][3]); }
;     const float rstd = 1.0f / sqrtf(wave_sum(s2) * (1.f / D) + LN_EPS);
; __global__ void __launch_bounds__(NT, 2) fwd(const Args args) {
;     ...
;             for (int m = m0; m < m1; m += 4) { u32x4 r[4][2];
; #pragma unroll
;                 for (int q = 0; q < 4; ++q) { const int mm = (m + q < m1) ? m + q : m1 - 1; row_raw(X + (size_t)mm * D, F.lane, r[q]); }
; #pragma unroll
;                 for (int q = 0; q < 4; ++q) if (m + q < m1) { f32x4 v[4]; row_unpack(r[q], v); row_ln(v, g, bb, F.lane);
.LBB0_1697:
	s_add_i32 s28, s6, 1
	s_add_i32 s27, s6, 2
	s_add_i32 s7, s6, 3
	s_waitcnt vmcnt(12)
	v_mov_b64_e32 v[32:33], v[136:137]
	v_mov_b64_e32 v[34:35], v[138:139]
	v_mov_b64_e32 v[28:29], v[140:141]
	v_mov_b64_e32 v[30:31], v[142:143]
	v_mov_b64_e32 v[20:21], v[144:145]
	v_mov_b64_e32 v[22:23], v[146:147]
	v_mov_b64_e32 v[24:25], v[148:149]
	v_mov_b64_e32 v[26:27], v[150:151]
	v_mov_b64_e32 v[12:13], v[152:153]
	v_mov_b64_e32 v[14:15], v[154:155]
	v_mov_b64_e32 v[16:17], v[156:157]
	v_mov_b64_e32 v[18:19], v[158:159]
	v_mov_b64_e32 v[4:5], v[160:161]
	v_mov_b64_e32 v[6:7], v[162:163]
	v_mov_b64_e32 v[8:9], v[164:165]
	v_mov_b64_e32 v[10:11], v[166:167]
	s_add_i32 s10, s6, 4
	s_min_i32 s10, s10, s12
	s_ashr_i32 s11, s10, 31
	s_lshl_b64 s[10:11], s[10:11], 11
	v_lshl_add_u64 v[170:171], v[52:53], 0, s[10:11]
	global_load_dwordx4 v[136:139], v[170:171], off
	global_load_dwordx4 v[140:143], v[170:171], off offset:1024
	s_add_i32 s10, s6, 5
	s_min_i32 s10, s10, s12
	s_ashr_i32 s11, s10, 31
	s_lshl_b64 s[10:11], s[10:11], 11
	v_lshl_add_u64 v[170:171], v[52:53], 0, s[10:11]
	global_load_dwordx4 v[144:147], v[170:171], off
	global_load_dwordx4 v[148:151], v[170:171], off offset:1024
	s_add_i32 s10, s6, 6
	s_min_i32 s10, s10, s12
	s_ashr_i32 s11, s10, 31
	s_lshl_b64 s[10:11], s[10:11], 11
	v_lshl_add_u64 v[170:171], v[52:53], 0, s[10:11]
	global_load_dwordx4 v[152:155], v[170:171], off
	global_load_dwordx4 v[156:159], v[170:171], off offset:1024
	s_add_i32 s10, s6, 7
	s_min_i32 s10, s10, s12
	s_ashr_i32 s11, s10, 31
	s_lshl_b64 s[10:11], s[10:11], 11
	v_lshl_add_u64 v[170:171], v[52:53], 0, s[10:11]
	global_load_dwordx4 v[160:163], v[170:171], off
	global_load_dwordx4 v[164:167], v[170:171], off offset:1024
	ds_read_b128 v[172:175], v94 offset:0
	ds_read_b128 v[176:179], v94 offset:16
	ds_read_b128 v[180:183], v94 offset:2048
	ds_read_b128 v[184:187], v94 offset:2064
	ds_read_b128 v[202:205], v94 offset:4096
	ds_read_b128 v[206:209], v94 offset:4112
	ds_read_b128 v[210:213], v94 offset:6144
	ds_read_b128 v[214:217], v94 offset:6160
	ds_read_b128 v[218:221], v94 offset:8192
	ds_read_b128 v[222:225], v94 offset:8208
	ds_read_b128 v[188:191], v94 offset:10240
	ds_read_b128 v[192:195], v94 offset:10256
	s_nop 0
	v_lshlrev_b32_e32 v78, 16, v30
	v_and_b32_e32 v82, 0xffff0000, v30
	v_lshlrev_b32_e32 v76, 16, v31
	v_and_b32_e32 v80, 0xffff0000, v31
	s_nop 0
	v_lshlrev_b32_e32 v31, 16, v33
	v_lshlrev_b32_e32 v30, 16, v32
	v_and_b32_e32 v33, 0xffff0000, v33
	v_and_b32_e32 v32, 0xffff0000, v32
	v_lshlrev_b32_e32 v86, 16, v28
	v_and_b32_e32 v87, 0xffff0000, v28
	v_lshlrev_b32_e32 v84, 16, v29
	v_and_b32_e32 v85, 0xffff0000, v29
	v_pk_add_f32 v[28:29], v[30:31], v[32:33]
	v_and_b32_e32 v37, 0xffff0000, v35
	v_add_f32_e32 v28, v28, v29
	v_add_f32_e32 v81, 0, v28
	v_lshlrev_b32_e32 v29, 16, v35
	v_lshlrev_b32_e32 v28, 16, v34
	v_and_b32_e32 v36, 0xffff0000, v34
	v_pk_add_f32 v[34:35], v[28:29], v[36:37]
	v_add_f32_e32 v79, v86, v87
	v_pk_add_f32 v[34:35], v[34:35], v[34:35] op_sel_hi:[0,1]
	v_add_f32_e32 v83, v84, v85
	v_mov_b32_e32 v77, v35
	v_pk_add_f32 v[38:39], v[78:79], v[82:83]
	v_pk_add_f32 v[34:35], v[76:77], v[80:81]
	s_nop 0
	v_pk_add_f32 v[34:35], v[38:39], v[34:35]
	s_nop 0
	v_add_f32_e32 v34, v34, v35
	v_mov_b32_e32 v35, v2
	s_nop 0
	v_add_f32_dpp v34, v34, v34 quad_perm:[1,0,3,2] row_mask:0xf bank_mask:0xf bound_ctrl:1
	s_nop 1
	v_add_f32_dpp v34, v34, v34 quad_perm:[2,3,0,1] row_mask:0xf bank_mask:0xf bound_ctrl:1
	s_nop 1
	v_add_f32_dpp v34, v34, v34 row_half_mirror row_mask:0xf bank_mask:0xf bound_ctrl:1
	s_nop 1
	v_add_f32_dpp v34, v34, v34 row_mirror row_mask:0xf bank_mask:0xf bound_ctrl:1
	s_nop 1
	v_mov_b32_dpp v35, v34 row_bcast:15 row_mask:0xa bank_mask:0xf
	v_add_f32_e32 v34, v34, v35
	v_mov_b32_e32 v35, v2
	s_nop 1
	v_mov_b32_dpp v35, v34 row_bcast:31 row_mask:0xc bank_mask:0xf
	v_add_f32_e32 v34, v34, v35
	s_nop 0
	v_readlane_b32 s10, v34, 63
	s_nop 1
	v_fmac_f32_e32 v33, s10, v236
	v_fmac_f32_e32 v32, s10, v236
	v_fmac_f32_e32 v31, s10, v236
	v_fmac_f32_e32 v30, s10, v236
	v_mul_f32_e32 v34, v32, v32
	v_mul_f32_e32 v35, v33, v33
	v_fmac_f32_e32 v34, v30, v30
	v_fmac_f32_e32 v35, v31, v31
	v_fmac_f32_e32 v37, s10, v236
	v_fmac_f32_e32 v36, s10, v236
	v_add_f32_e32 v34, v34, v35
	v_fmac_f32_e32 v29, s10, v236
	v_fmac_f32_e32 v28, s10, v236
	v_mul_f32_e32 v35, v36, v36
	v_mul_f32_e32 v38, v37, v37
	v_fmac_f32_e32 v35, v28, v28
	v_fmac_f32_e32 v38, v29, v29
; __device__ __forceinline__ float wave_sum(float v) { return rdlane(dpp_sum63(v), 63); }
; __device__ __forceinline__ void row_ln(f32x4 (&v)[4], const float* g, const float* b, int lane) {
;     float s = 0.f;
; #pragma unroll
;     for (int j = 0; j < 4; ++j) s += (v[j][0] + v[j][1]) + (v[j][2] + v[j][3]);
;     const float mean = wave_sum(s) * (1.f / D); float s2 = 0.f;
; #pragma unroll
;     for (int j = 0; j < 4; ++j) { v[j] = v[j] - mean; s2 += (v[j][0] * v[j][0] + v[j][1] * v[j][1]) + (v[j][2] * v[j][2] + v[j][3] * v[j][3]); }
;     const float rstd = 1.0f / sqrtf(wave_sum(s2) * (1.f / D) + LN_EPS);
; #pragma unroll
;     for (int j = 0; j < 4; ++j) { const f32x4 gg = *(const f32x4*)(g + RCOL(lane, j)), bb = *(const f32x4*)(b + RCOL(lane, j)); v[j] = v[j] * rstd * gg + bb; }
; }
; __global__ void __launch_bounds__(NT, 2) fwd(const Args args) {
;     ...
;                 for (int q = 0; q < 4; ++q) if (m + q < m1) { f32x4 v[4]; row_unpack(r[q], v); row_ln(v, g, bb, F.lane);
;                     if (L + 1 < DEPTH) row_finalize(A, F, m + q, v, L + 1);
;                     else {
; #pragma unroll
;                         for (int j = 0; j < 4; ++j) *(f32x4*)(F.out + O_Y + (size_t)(m + q) * D + RCOL(F.lane, j)) = v[j]; } } }
	v_add_f32_e32 v35, v35, v38
	v_fmac_f32_e32 v85, s10, v236
	v_fmac_f32_e32 v87, s10, v236
	v_add_f32_e32 v34, v34, v35
	v_fmac_f32_e32 v84, s10, v236
	v_fmac_f32_e32 v86, s10, v236
	v_mul_f32_e32 v35, v87, v87
	v_mul_f32_e32 v38, v85, v85
	v_fmac_f32_e32 v35, v86, v86
	v_fmac_f32_e32 v38, v84, v84
	v_add_f32_e32 v35, v35, v38
	v_fmac_f32_e32 v80, s10, v236
	v_fmac_f32_e32 v82, s10, v236
	v_add_f32_e32 v34, v35, v34
	v_fmac_f32_e32 v76, s10, v236
	v_fmac_f32_e32 v78, s10, v236
	v_mul_f32_e32 v35, v82, v82
	v_mul_f32_e32 v38, v80, v80
	v_fmac_f32_e32 v35, v78, v78
	v_fmac_f32_e32 v38, v76, v76
	v_add_f32_e32 v35, v35, v38
	v_add_f32_e32 v34, v35, v34
	v_mov_b32_e32 v35, v2
	v_mov_b32_e32 v79, v82
	v_add_f32_dpp v34, v34, v34 quad_perm:[1,0,3,2] row_mask:0xf bank_mask:0xf bound_ctrl:1
	v_mov_b32_e32 v77, v80
	s_nop 0
	v_add_f32_dpp v34, v34, v34 quad_perm:[2,3,0,1] row_mask:0xf bank_mask:0xf bound_ctrl:1
	s_nop 1
	v_add_f32_dpp v34, v34, v34 row_half_mirror row_mask:0xf bank_mask:0xf bound_ctrl:1
	s_nop 1
	v_add_f32_dpp v34, v34, v34 row_mirror row_mask:0xf bank_mask:0xf bound_ctrl:1
	s_nop 1
	v_mov_b32_dpp v35, v34 row_bcast:15 row_mask:0xa bank_mask:0xf
	v_add_f32_e32 v34, v34, v35
	v_mov_b32_e32 v35, v2
	s_nop 1
	v_mov_b32_dpp v35, v34 row_bcast:31 row_mask:0xc bank_mask:0xf
	v_add_f32_e32 v34, v34, v35
	s_nop 0
	v_readlane_b32 s10, v34, 63
	s_nop 1
	v_fma_f32 v34, s10, v237, v252
	v_cmp_gt_f32_e32 vcc, s31, v34
	v_mul_f32_e32 v35, 0x4f800000, v34
	s_nop 0
	v_cndmask_b32_e32 v34, v34, v35, vcc
	v_sqrt_f32_e32 v35, v34
	s_nop 0
	v_add_u32_e32 v38, -1, v35
	v_fma_f32 v39, -v38, v35, v34
	v_cmp_ge_f32_e64 s[54:55], 0, v39
	v_add_u32_e32 v39, 1, v35
	s_nop 0
	v_cndmask_b32_e64 v38, v35, v38, s[54:55]
	v_fma_f32 v35, -v39, v35, v34
	v_cmp_lt_f32_e64 s[54:55], 0, v35
	s_nop 1
	v_cndmask_b32_e64 v35, v38, v39, s[54:55]
	v_mul_f32_e32 v38, 0x37800000, v35
	v_cndmask_b32_e32 v35, v35, v38, vcc
	v_cmp_class_f32_e32 vcc, v34, v234
	s_nop 1
	v_cndmask_b32_e32 v34, v35, v34, vcc
	v_div_scale_f32 v35, s[10:11], v34, v34, 1.0
	v_rcp_f32_e32 v38, v35
	s_mov_b64 s[10:11], -1
	v_fma_f32 v39, -v35, v38, 1.0
	v_fmac_f32_e32 v38, v39, v38
	v_div_scale_f32 v39, vcc, 1.0, v34, 1.0
	v_mul_f32_e32 v40, v39, v38
	v_fma_f32 v41, -v35, v40, v39
	v_fmac_f32_e32 v40, v41, v38
	v_fma_f32 v35, -v35, v40, v39
	v_div_fmas_f32 v35, v35, v38, v40
	v_mov_b64_e32 v[38:39], v[108:109]
	v_mov_b64_e32 v[40:41], v[110:111]
	v_mov_b64_e32 v[42:43], v[104:105]
	v_mov_b64_e32 v[44:45], v[106:107]
	v_mov_b64_e32 v[46:47], v[124:125]
	v_mov_b64_e32 v[48:49], v[126:127]
	v_mov_b64_e32 v[90:91], v[120:121]
	v_mov_b64_e32 v[92:93], v[122:123]
	v_div_fixup_f32 v88, v35, v34, 1.0
	v_mov_b32_e32 v35, v32
	v_mov_b32_e32 v32, v31
	v_mov_b32_e32 v34, v30
	v_pk_mul_f32 v[30:31], v[32:33], v[88:89] op_sel_hi:[1,0]
	v_pk_mul_f32 v[50:51], v[34:35], v[88:89] op_sel_hi:[1,0]
	v_pk_mul_f32 v[86:87], v[86:87], v[88:89] op_sel_hi:[1,0]
	v_pk_mul_f32 v[84:85], v[84:85], v[88:89] op_sel_hi:[1,0]
	s_andn2_b64 vcc, exec, s[4:5]
	s_nop 0
	v_pk_fma_f32 v[34:35], v[44:45], v[30:31], v[92:93]
	v_mov_b32_e32 v30, v28
	v_mov_b32_e32 v31, v36
	v_mov_b32_e32 v36, v29
	v_pk_fma_f32 v[32:33], v[42:43], v[50:51], v[90:91]
	v_pk_mul_f32 v[42:43], v[30:31], v[88:89] op_sel_hi:[1,0]
	v_pk_mul_f32 v[28:29], v[36:37], v[88:89] op_sel_hi:[1,0]
	s_nop 0
	v_pk_fma_f32 v[30:31], v[40:41], v[28:29], v[48:49]
	v_pk_fma_f32 v[28:29], v[38:39], v[42:43], v[46:47]
	v_mov_b64_e32 v[36:37], v[116:117]
	v_mov_b64_e32 v[38:39], v[118:119]
	v_mov_b64_e32 v[44:45], v[112:113]
	v_mov_b64_e32 v[46:47], v[114:115]
	v_mov_b64_e32 v[40:41], v[132:133]
	v_mov_b64_e32 v[42:43], v[134:135]
	v_mov_b64_e32 v[48:49], v[128:129]
	v_mov_b64_e32 v[50:51], v[130:131]
	s_nop 0
	v_pk_fma_f32 v[44:45], v[44:45], v[86:87], v[48:49]
	v_pk_mul_f32 v[48:49], v[78:79], v[88:89] op_sel_hi:[1,0]
	v_pk_fma_f32 v[46:47], v[46:47], v[84:85], v[50:51]
	v_pk_mul_f32 v[50:51], v[76:77], v[88:89] op_sel_hi:[1,0]
	v_pk_fma_f32 v[36:37], v[36:37], v[48:49], v[40:41]
	v_cndmask_b32_e64 v40, 0, 1, s[4:5]
	v_pk_fma_f32 v[38:39], v[38:39], v[50:51], v[42:43]
	v_cmp_ne_u32_e64 s[54:55], 1, v40
	s_cbranch_vccnz .LBB0_1700
	v_lshl_add_u64 v[40:41], s[14:15], 0, v[54:55]
	global_store_dwordx4 v[40:41], v[32:35], off
	global_store_dwordx4 v[40:41], v[28:31], off offset:16
	global_store_dwordx4 v[40:41], v[44:47], off offset:2048
	global_store_dwordx4 v[40:41], v[36:39], off offset:2064
	s_cbranch_execz .LBB0_1701

; #define LAS __attribute__((address_space(3)))
; __device__ __forceinline__ float wave_sum(float v) { return rdlane(dpp_sum63(v), 63); }
; __device__ __forceinline__ void row_finalize(CArgs& A, Frame& F, int m, const f32x4 (&v)[4], int Ln) {
;     row_store_bf(WSP(bf16, WS_X) + (size_t)m * D, F.lane, v);
;     const LAS float* wig = (const LAS float*)(F.lds + WIG_OFF); const float* b_in = A.in[10] + (size_t)Ln * DIN + 3072;
;     float r[8];
; #pragma unroll
;     for (int c = 0; c < 8; ++c) { float s = 0.f;
; #pragma unroll
;         for (int j = 0; j < 4; ++j) { const f32x4 w = *(const LAS f32x4*)(wig + c * 1024 + RCOL(F.lane, j)); s += (v[j][0] * w[0] + v[j][1] * w[1]) + (v[j][2] * w[2] + v[j][3] * w[3]); }
;         r[c] = wave_sum(s); if (c & 1) asm volatile("" ::: "memory"); }
.LBB0_1701:
	v_lshl_add_u64 v[238:239], s[58:59], 0, v[62:63]
	s_mov_b64 s[10:11], 0x7680000
	v_cvt_pk_bf16_f32 v240, v32, v33
	v_cvt_pk_bf16_f32 v241, v34, v35
	v_cvt_pk_bf16_f32 v242, v28, v29
	v_cvt_pk_bf16_f32 v243, v30, v31
	v_lshl_add_u64 v[238:239], v[238:239], 0, s[10:11]
	v_cvt_pk_bf16_f32 v244, v44, v45
	v_cvt_pk_bf16_f32 v245, v46, v47
	v_cvt_pk_bf16_f32 v246, v36, v37
	v_cvt_pk_bf16_f32 v247, v38, v39
	global_store_dwordx4 v[238:239], v[240:243], off
	global_store_dwordx4 v[238:239], v[244:247], off offset:1024
	v_lshl_add_u64 v[196:197], s[58:59], 0, v[60:61]
	s_waitcnt lgkmcnt(8)
	v_mul_f32_e32 v249, v33, v173
	v_mul_f32_e32 v250, v35, v175
	v_fmac_f32_e32 v249, v32, v172
	v_fmac_f32_e32 v250, v34, v174
	v_add_f32_e32 v249, v249, v250
	v_add_f32_e32 v227, 0, v249
	v_mul_f32_e32 v249, v29, v177
	v_mul_f32_e32 v250, v31, v179
	v_fmac_f32_e32 v249, v28, v176
	v_fmac_f32_e32 v250, v30, v178
	v_add_f32_e32 v249, v249, v250
	v_add_f32_e32 v227, v227, v249
	v_mul_f32_e32 v249, v45, v181
	v_mul_f32_e32 v250, v47, v183
	v_fmac_f32_e32 v249, v44, v180
	v_fmac_f32_e32 v250, v46, v182
	v_add_f32_e32 v249, v249, v250
	v_add_f32_e32 v227, v227, v249
	v_mul_f32_e32 v249, v37, v185
	v_mul_f32_e32 v250, v39, v187
	v_fmac_f32_e32 v249, v36, v184
	v_fmac_f32_e32 v250, v38, v186
	v_add_f32_e32 v249, v249, v250
	v_add_f32_e32 v227, v227, v249
	ds_read_b128 v[172:175], v94 offset:12288
	ds_read_b128 v[176:179], v94 offset:12304
	ds_read_b128 v[180:183], v94 offset:14336
	ds_read_b128 v[184:187], v94 offset:14352
	s_waitcnt lgkmcnt(8)
	v_mul_f32_e32 v249, v33, v203
	v_mul_f32_e32 v250, v35, v205
	v_fmac_f32_e32 v249, v32, v202
	v_fmac_f32_e32 v250, v34, v204
	v_add_f32_e32 v249, v249, v250
	v_add_f32_e32 v228, 0, v249
	v_mul_f32_e32 v249, v29, v207
	v_mul_f32_e32 v250, v31, v209
	v_fmac_f32_e32 v249, v28, v206
	v_fmac_f32_e32 v250, v30, v208
	v_add_f32_e32 v249, v249, v250
	v_add_f32_e32 v228, v228, v249
	v_mul_f32_e32 v249, v45, v211
	v_mul_f32_e32 v250, v47, v213
	v_fmac_f32_e32 v249, v44, v210
	v_fmac_f32_e32 v250, v46, v212
	v_add_f32_e32 v249, v249, v250
	v_add_f32_e32 v228, v228, v249
	v_mul_f32_e32 v249, v37, v215
	v_mul_f32_e32 v250, v39, v217
	v_fmac_f32_e32 v249, v36, v214
	v_fmac_f32_e32 v250, v38, v216
	v_add_f32_e32 v249, v249, v250
	v_add_f32_e32 v228, v228, v249
	ds_read_b128 v[202:205], v94 offset:16384
	ds_read_b128 v[206:209], v94 offset:16400
	ds_read_b128 v[210:213], v94 offset:18432
	ds_read_b128 v[214:217], v94 offset:18448
	s_waitcnt lgkmcnt(8)
	v_mul_f32_e32 v249, v33, v219
	v_mul_f32_e32 v250, v35, v221
	v_fmac_f32_e32 v249, v32, v218
	v_fmac_f32_e32 v250, v34, v220
	v_add_f32_e32 v249, v249, v250
	v_add_f32_e32 v229, 0, v249
	v_mul_f32_e32 v249, v29, v223
	v_mul_f32_e32 v250, v31, v225
	v_fmac_f32_e32 v249, v28, v222
	v_fmac_f32_e32 v250, v30, v224
	v_add_f32_e32 v249, v249, v250
	v_add_f32_e32 v229, v229, v249
	v_mul_f32_e32 v249, v45, v189
	v_mul_f32_e32 v250, v47, v191
	v_fmac_f32_e32 v249, v44, v188
	v_fmac_f32_e32 v250, v46, v190
	v_add_f32_e32 v249, v249, v250
	v_add_f32_e32 v229, v229, v249
	v_mul_f32_e32 v249, v37, v193
	v_mul_f32_e32 v250, v39, v195
	v_fmac_f32_e32 v249, v36, v192
	v_fmac_f32_e32 v250, v38, v194
	v_add_f32_e32 v249, v249, v250
	v_add_f32_e32 v229, v229, v249
	ds_read_b128 v[218:221], v94 offset:20480
	ds_read_b128 v[222:225], v94 offset:20496
	ds_read_b128 v[188:191], v94 offset:22528
	ds_read_b128 v[192:195], v94 offset:22544
	s_waitcnt lgkmcnt(8)
	v_mul_f32_e32 v249, v33, v173
	v_mul_f32_e32 v250, v35, v175
	v_fmac_f32_e32 v249, v32, v172
	v_fmac_f32_e32 v250, v34, v174
	v_add_f32_e32 v249, v249, v250
	v_add_f32_e32 v230, 0, v249
	v_mul_f32_e32 v249, v29, v177
	v_mul_f32_e32 v250, v31, v179
	v_fmac_f32_e32 v249, v28, v176
	v_fmac_f32_e32 v250, v30, v178
	v_add_f32_e32 v249, v249, v250
	v_add_f32_e32 v230, v230, v249
	v_mul_f32_e32 v249, v45, v181
	v_mul_f32_e32 v250, v47, v183
	v_fmac_f32_e32 v249, v44, v180
	v_fmac_f32_e32 v250, v46, v182
	v_add_f32_e32 v249, v249, v250
	v_add_f32_e32 v230, v230, v249
	v_mul_f32_e32 v249, v37, v185
	v_mul_f32_e32 v250, v39, v187
	v_fmac_f32_e32 v249, v36, v184
	v_fmac_f32_e32 v250, v38, v186
	v_add_f32_e32 v249, v249, v250
	v_add_f32_e32 v230, v230, v249
	ds_read_b128 v[172:175], v94 offset:24576
	ds_read_b128 v[176:179], v94 offset:24592
	ds_read_b128 v[180:183], v94 offset:26624
	ds_read_b128 v[184:187], v94 offset:26640
	s_waitcnt lgkmcnt(8)
	v_mul_f32_e32 v249, v33, v203
	v_mul_f32_e32 v250, v35, v205
	v_fmac_f32_e32 v249, v32, v202
	v_fmac_f32_e32 v250, v34, v204
	v_add_f32_e32 v249, v249, v250
	v_add_f32_e32 v231, 0, v249
	v_mul_f32_e32 v249, v29, v207
	v_mul_f32_e32 v250, v31, v209
	v_fmac_f32_e32 v249, v28, v206
	v_fmac_f32_e32 v250, v30, v208
	v_add_f32_e32 v249, v249, v250
	v_add_f32_e32 v231, v231, v249
	v_mul_f32_e32 v249, v45, v211
	v_mul_f32_e32 v250, v47, v213
	v_fmac_f32_e32 v249, v44, v210
	v_fmac_f32_e32 v250, v46, v212
	v_add_f32_e32 v249, v249, v250
	v_add_f32_e32 v231, v231, v249
	v_mul_f32_e32 v249, v37, v215
	v_mul_f32_e32 v250, v39, v217
	v_fmac_f32_e32 v249, v36, v214
	v_fmac_f32_e32 v250, v38, v216
	v_add_f32_e32 v249, v249, v250
	v_add_f32_e32 v231, v231, v249
	ds_read_b128 v[202:205], v94 offset:28672
	ds_read_b128 v[206:209], v94 offset:28688
	ds_read_b128 v[210:213], v94 offset:30720
	ds_read_b128 v[214:217], v94 offset:30736
	s_waitcnt lgkmcnt(8)
; #define LAS __attribute__((address_space(3)))
; __device__ __forceinline__ float wave_sum(float v) { return rdlane(dpp_sum63(v), 63); }
; __device__ __forceinline__ void row_finalize(CArgs& A, Frame& F, int m, const f32x4 (&v)[4], int Ln) {
;     ...
;     for (int c = 0; c < 8; ++c) { float s = 0.f;
; #pragma unroll
;         for (int j = 0; j < 4; ++j) { const f32x4 w = *(const LAS f32x4*)(wig + c * 1024 + RCOL(F.lane, j)); s += (v[j][0] * w[0] + v[j][1] * w[1]) + (v[j][2] * w[2] + v[j][3] * w[3]); }
;         r[c] = wave_sum(s); if (c & 1) asm volatile("" ::: "memory"); }
;     if (F.lane < 8) { float x = r[0];
; #pragma unroll
;         for (int c = 1; c < 8; ++c) x = (F.lane == c) ? r[c] : x;
;         WSP(float, WS_IGFG)[(size_t)m * 8 + F.lane] = x + b_in[F.lane]; }
	v_mul_f32_e32 v249, v33, v219
	v_mul_f32_e32 v250, v35, v221
	v_fmac_f32_e32 v249, v32, v218
	v_fmac_f32_e32 v250, v34, v220
	v_add_f32_e32 v249, v249, v250
	v_add_f32_e32 v232, 0, v249
	v_mul_f32_e32 v249, v29, v223
	v_mul_f32_e32 v250, v31, v225
	v_fmac_f32_e32 v249, v28, v222
	v_fmac_f32_e32 v250, v30, v224
	v_add_f32_e32 v249, v249, v250
	v_add_f32_e32 v232, v232, v249
	v_mul_f32_e32 v249, v45, v189
	v_mul_f32_e32 v250, v47, v191
	v_fmac_f32_e32 v249, v44, v188
	v_fmac_f32_e32 v250, v46, v190
	v_add_f32_e32 v249, v249, v250
	v_add_f32_e32 v232, v232, v249
	v_mul_f32_e32 v249, v37, v193
	v_mul_f32_e32 v250, v39, v195
	v_fmac_f32_e32 v249, v36, v192
	v_fmac_f32_e32 v250, v38, v194
	v_add_f32_e32 v249, v249, v250
	v_add_f32_e32 v232, v232, v249
	s_waitcnt lgkmcnt(4)
	v_mul_f32_e32 v249, v33, v173
	v_mul_f32_e32 v250, v35, v175
	v_fmac_f32_e32 v249, v32, v172
	v_fmac_f32_e32 v250, v34, v174
	v_add_f32_e32 v249, v249, v250
	v_add_f32_e32 v233, 0, v249
	v_mul_f32_e32 v249, v29, v177
	v_mul_f32_e32 v250, v31, v179
	v_fmac_f32_e32 v249, v28, v176
	v_fmac_f32_e32 v250, v30, v178
	v_add_f32_e32 v249, v249, v250
	v_add_f32_e32 v233, v233, v249
	v_mul_f32_e32 v249, v45, v181
	v_mul_f32_e32 v250, v47, v183
	v_fmac_f32_e32 v249, v44, v180
	v_fmac_f32_e32 v250, v46, v182
	v_add_f32_e32 v249, v249, v250
	v_add_f32_e32 v233, v233, v249
	v_mul_f32_e32 v249, v37, v185
	v_mul_f32_e32 v250, v39, v187
	v_fmac_f32_e32 v249, v36, v184
	v_fmac_f32_e32 v250, v38, v186
	v_add_f32_e32 v249, v249, v250
	v_add_f32_e32 v233, v233, v249
	s_waitcnt lgkmcnt(0)
	v_mul_f32_e32 v249, v33, v203
	v_mul_f32_e32 v250, v35, v205
	v_fmac_f32_e32 v249, v32, v202
	v_fmac_f32_e32 v250, v34, v204
	v_add_f32_e32 v249, v249, v250
	v_add_f32_e32 v248, 0, v249
	v_mul_f32_e32 v249, v29, v207
	v_mul_f32_e32 v250, v31, v209
	v_fmac_f32_e32 v249, v28, v206
	v_fmac_f32_e32 v250, v30, v208
	v_add_f32_e32 v249, v249, v250
	v_add_f32_e32 v248, v248, v249
	v_mul_f32_e32 v249, v45, v211
	v_mul_f32_e32 v250, v47, v213
	v_fmac_f32_e32 v249, v44, v210
	v_fmac_f32_e32 v250, v46, v212
	v_add_f32_e32 v249, v249, v250
	v_add_f32_e32 v248, v248, v249
	v_mul_f32_e32 v249, v37, v215
	v_mul_f32_e32 v250, v39, v217
	v_fmac_f32_e32 v249, v36, v214
	v_fmac_f32_e32 v250, v38, v216
	v_add_f32_e32 v249, v249, v250
	v_add_f32_e32 v248, v248, v249
	v_add_f32_dpp v227, v227, v227 quad_perm:[1,0,3,2] row_mask:0xf bank_mask:0xf bound_ctrl:1
	v_add_f32_dpp v228, v228, v228 quad_perm:[1,0,3,2] row_mask:0xf bank_mask:0xf bound_ctrl:1
	v_add_f32_dpp v229, v229, v229 quad_perm:[1,0,3,2] row_mask:0xf bank_mask:0xf bound_ctrl:1
	v_add_f32_dpp v230, v230, v230 quad_perm:[1,0,3,2] row_mask:0xf bank_mask:0xf bound_ctrl:1
	v_add_f32_dpp v231, v231, v231 quad_perm:[1,0,3,2] row_mask:0xf bank_mask:0xf bound_ctrl:1
	v_add_f32_dpp v232, v232, v232 quad_perm:[1,0,3,2] row_mask:0xf bank_mask:0xf bound_ctrl:1
	v_add_f32_dpp v233, v233, v233 quad_perm:[1,0,3,2] row_mask:0xf bank_mask:0xf bound_ctrl:1
	v_add_f32_dpp v248, v248, v248 quad_perm:[1,0,3,2] row_mask:0xf bank_mask:0xf bound_ctrl:1
	v_add_f32_dpp v227, v227, v227 quad_perm:[2,3,0,1] row_mask:0xf bank_mask:0xf bound_ctrl:1
	v_add_f32_dpp v228, v228, v228 quad_perm:[2,3,0,1] row_mask:0xf bank_mask:0xf bound_ctrl:1
	v_add_f32_dpp v229, v229, v229 quad_perm:[2,3,0,1] row_mask:0xf bank_mask:0xf bound_ctrl:1
	v_add_f32_dpp v230, v230, v230 quad_perm:[2,3,0,1] row_mask:0xf bank_mask:0xf bound_ctrl:1
	v_add_f32_dpp v231, v231, v231 quad_perm:[2,3,0,1] row_mask:0xf bank_mask:0xf bound_ctrl:1
	v_add_f32_dpp v232, v232, v232 quad_perm:[2,3,0,1] row_mask:0xf bank_mask:0xf bound_ctrl:1
	v_add_f32_dpp v233, v233, v233 quad_perm:[2,3,0,1] row_mask:0xf bank_mask:0xf bound_ctrl:1
	v_add_f32_dpp v248, v248, v248 quad_perm:[2,3,0,1] row_mask:0xf bank_mask:0xf bound_ctrl:1
	v_add_f32_dpp v227, v227, v227 row_half_mirror row_mask:0xf bank_mask:0xf bound_ctrl:1
	v_add_f32_dpp v228, v228, v228 row_half_mirror row_mask:0xf bank_mask:0xf bound_ctrl:1
	v_add_f32_dpp v229, v229, v229 row_half_mirror row_mask:0xf bank_mask:0xf bound_ctrl:1
	v_add_f32_dpp v230, v230, v230 row_half_mirror row_mask:0xf bank_mask:0xf bound_ctrl:1
	v_add_f32_dpp v231, v231, v231 row_half_mirror row_mask:0xf bank_mask:0xf bound_ctrl:1
	v_add_f32_dpp v232, v232, v232 row_half_mirror row_mask:0xf bank_mask:0xf bound_ctrl:1
	v_add_f32_dpp v233, v233, v233 row_half_mirror row_mask:0xf bank_mask:0xf bound_ctrl:1
	v_add_f32_dpp v248, v248, v248 row_half_mirror row_mask:0xf bank_mask:0xf bound_ctrl:1
	v_add_f32_dpp v227, v227, v227 row_mirror row_mask:0xf bank_mask:0xf bound_ctrl:1
	v_add_f32_dpp v228, v228, v228 row_mirror row_mask:0xf bank_mask:0xf bound_ctrl:1
	v_add_f32_dpp v229, v229, v229 row_mirror row_mask:0xf bank_mask:0xf bound_ctrl:1
	v_add_f32_dpp v230, v230, v230 row_mirror row_mask:0xf bank_mask:0xf bound_ctrl:1
	v_add_f32_dpp v231, v231, v231 row_mirror row_mask:0xf bank_mask:0xf bound_ctrl:1
	v_add_f32_dpp v232, v232, v232 row_mirror row_mask:0xf bank_mask:0xf bound_ctrl:1
	v_add_f32_dpp v233, v233, v233 row_mirror row_mask:0xf bank_mask:0xf bound_ctrl:1
	v_add_f32_dpp v248, v248, v248 row_mirror row_mask:0xf bank_mask:0xf bound_ctrl:1
	v_add_f32_dpp v227, v227, v227 row_bcast:15 row_mask:0xa bank_mask:0xf
	v_add_f32_dpp v228, v228, v228 row_bcast:15 row_mask:0xa bank_mask:0xf
	v_add_f32_dpp v229, v229, v229 row_bcast:15 row_mask:0xa bank_mask:0xf
	v_add_f32_dpp v230, v230, v230 row_bcast:15 row_mask:0xa bank_mask:0xf
	v_add_f32_dpp v231, v231, v231 row_bcast:15 row_mask:0xa bank_mask:0xf
	v_add_f32_dpp v232, v232, v232 row_bcast:15 row_mask:0xa bank_mask:0xf
	v_add_f32_dpp v233, v233, v233 row_bcast:15 row_mask:0xa bank_mask:0xf
	v_add_f32_dpp v248, v248, v248 row_bcast:15 row_mask:0xa bank_mask:0xf
	v_add_f32_dpp v227, v227, v227 row_bcast:31 row_mask:0xc bank_mask:0xf
	v_add_f32_dpp v228, v228, v228 row_bcast:31 row_mask:0xc bank_mask:0xf
	v_add_f32_dpp v229, v229, v229 row_bcast:31 row_mask:0xc bank_mask:0xf
	v_add_f32_dpp v230, v230, v230 row_bcast:31 row_mask:0xc bank_mask:0xf
	v_add_f32_dpp v231, v231, v231 row_bcast:31 row_mask:0xc bank_mask:0xf
	v_add_f32_dpp v232, v232, v232 row_bcast:31 row_mask:0xc bank_mask:0xf
	v_add_f32_dpp v233, v233, v233 row_bcast:31 row_mask:0xc bank_mask:0xf
	v_add_f32_dpp v248, v248, v248 row_bcast:31 row_mask:0xc bank_mask:0xf
	v_readlane_b32 s29, v227, 63
	v_readlane_b32 s36, v228, 63
	v_readlane_b32 s37, v229, 63
	v_readlane_b32 s56, v230, 63
	v_readlane_b32 s57, v231, 63
	v_readlane_b32 s60, v232, 63
	v_readlane_b32 s61, v233, 63
	v_readlane_b32 s64, v248, 63
	v_writelane_b32 v251, s29, 0
	v_writelane_b32 v251, s36, 1
	v_writelane_b32 v251, s37, 2
	v_writelane_b32 v251, s56, 3
	v_writelane_b32 v251, s57, 4
	v_writelane_b32 v251, s60, 5
	v_writelane_b32 v251, s61, 6
	v_writelane_b32 v251, s64, 7
	s_and_saveexec_b64 s[10:11], s[38:39]
	v_add_f32_e32 v251, v251, v168
	global_store_dword v[196:197], v251, off

; __device__ __forceinline__ float wave_sum(float v) { return rdlane(dpp_sum63(v), 63); }
; __device__ __forceinline__ void row_ln(f32x4 (&v)[4], const float* g, const float* b, int lane) {
;     float s = 0.f;
; #pragma unroll
;     for (int j = 0; j < 4; ++j) s += (v[j][0] + v[j][1]) + (v[j][2] + v[j][3]);
;     const float mean = wave_sum(s) * (1.f / D); float s2 = 0.f;
; #pragma unroll
;     for (int j = 0; j < 4; ++j) { v[j] = v[j] - mean; s2 += (v[j][0] * v[j][0] + v[j][1] * v[j][1]) + (v[j][2] * v[j][2] + v[j][3] * v[j][3]); }
;     const float rstd = 1.0f / sqrtf(wave_sum(s2) * (1.f / D) + LN_EPS);
; #pragma unroll
;     for (int j = 0; j < 4; ++j) { const f32x4 gg = *(const f32x4*)(g + RCOL(lane, j)), bb = *(const f32x4*)(b + RCOL(lane, j)); v[j] = v[j] * rstd * gg + bb; }
; }
; __global__ void __launch_bounds__(NT, 2) fwd(const Args args) {
;     ...
;                 for (int q = 0; q < 4; ++q) if (m + q < m1) { f32x4 v[4]; row_unpack(r[q], v); row_ln(v, g, bb, F.lane);
;                     if (L + 1 < DEPTH) row_finalize(A, F, m + q, v, L + 1);
.LBB0_1704:
	ds_read_b128 v[172:175], v94 offset:0
	ds_read_b128 v[176:179], v94 offset:16
	ds_read_b128 v[180:183], v94 offset:2048
	ds_read_b128 v[184:187], v94 offset:2064
	ds_read_b128 v[202:205], v94 offset:4096
	ds_read_b128 v[206:209], v94 offset:4112
	ds_read_b128 v[210:213], v94 offset:6144
	ds_read_b128 v[214:217], v94 offset:6160
	ds_read_b128 v[218:221], v94 offset:8192
	ds_read_b128 v[222:225], v94 offset:8208
	ds_read_b128 v[188:191], v94 offset:10240
	ds_read_b128 v[192:195], v94 offset:10256
	v_lshlrev_b32_e32 v78, 16, v24
	v_and_b32_e32 v79, 0xffff0000, v24
	v_lshlrev_b32_e32 v76, 16, v25
	v_and_b32_e32 v77, 0xffff0000, v25
	v_lshlrev_b32_e32 v25, 16, v21
	v_lshlrev_b32_e32 v24, 16, v20
	v_and_b32_e32 v21, 0xffff0000, v21
	v_and_b32_e32 v20, 0xffff0000, v20
	v_lshlrev_b32_e32 v46, 16, v26
	v_and_b32_e32 v50, 0xffff0000, v26
	v_lshlrev_b32_e32 v44, 16, v27
	v_and_b32_e32 v48, 0xffff0000, v27
	v_pk_add_f32 v[26:27], v[24:25], v[20:21]
	v_lshlrev_b32_e32 v29, 16, v23
	v_add_f32_e32 v26, v26, v27
	v_lshlrev_b32_e32 v28, 16, v22
	v_and_b32_e32 v23, 0xffff0000, v23
	v_and_b32_e32 v22, 0xffff0000, v22
	v_add_f32_e32 v49, 0, v26
	v_pk_add_f32 v[26:27], v[28:29], v[22:23]
	v_add_f32_e32 v47, v78, v79
	v_pk_add_f32 v[26:27], v[26:27], v[26:27] op_sel_hi:[0,1]
	v_add_f32_e32 v51, v76, v77
	v_mov_b32_e32 v45, v27
	v_pk_add_f32 v[30:31], v[46:47], v[50:51]
	v_pk_add_f32 v[26:27], v[44:45], v[48:49]
	s_nop 0
	v_pk_add_f32 v[26:27], v[30:31], v[26:27]
	s_nop 0
	v_add_f32_e32 v26, v26, v27
	v_mov_b32_e32 v27, v2
	s_nop 0
	v_add_f32_dpp v26, v26, v26 quad_perm:[1,0,3,2] row_mask:0xf bank_mask:0xf bound_ctrl:1
	s_nop 1
	v_add_f32_dpp v26, v26, v26 quad_perm:[2,3,0,1] row_mask:0xf bank_mask:0xf bound_ctrl:1
	s_nop 1
	v_add_f32_dpp v26, v26, v26 row_half_mirror row_mask:0xf bank_mask:0xf bound_ctrl:1
	s_nop 1
	v_add_f32_dpp v26, v26, v26 row_mirror row_mask:0xf bank_mask:0xf bound_ctrl:1
	s_nop 1
	v_mov_b32_dpp v27, v26 row_bcast:15 row_mask:0xa bank_mask:0xf
	v_add_f32_e32 v26, v26, v27
	v_mov_b32_e32 v27, v2
	s_nop 1
	v_mov_b32_dpp v27, v26 row_bcast:31 row_mask:0xc bank_mask:0xf
	v_add_f32_e32 v26, v26, v27
	s_nop 0
	v_readlane_b32 s10, v26, 63
	s_nop 1
	v_fmac_f32_e32 v21, s10, v236
	v_fmac_f32_e32 v20, s10, v236
	v_fmac_f32_e32 v25, s10, v236
	v_fmac_f32_e32 v24, s10, v236
	v_mul_f32_e32 v26, v20, v20
	v_mul_f32_e32 v27, v21, v21
	v_fmac_f32_e32 v26, v24, v24
	v_fmac_f32_e32 v27, v25, v25
	v_fmac_f32_e32 v23, s10, v236
	v_fmac_f32_e32 v22, s10, v236
	v_add_f32_e32 v26, v26, v27
	v_fmac_f32_e32 v29, s10, v236
	v_fmac_f32_e32 v28, s10, v236
	v_mul_f32_e32 v27, v22, v22
	v_mul_f32_e32 v30, v23, v23
	v_fmac_f32_e32 v27, v28, v28
	v_fmac_f32_e32 v30, v29, v29
	v_add_f32_e32 v27, v27, v30
	v_fmac_f32_e32 v77, s10, v236
	v_fmac_f32_e32 v79, s10, v236
	v_add_f32_e32 v26, v26, v27
	v_fmac_f32_e32 v76, s10, v236
	v_fmac_f32_e32 v78, s10, v236
	v_mul_f32_e32 v27, v79, v79
	v_mul_f32_e32 v30, v77, v77
	v_fmac_f32_e32 v27, v78, v78
	v_fmac_f32_e32 v30, v76, v76
	v_add_f32_e32 v27, v27, v30
	v_fmac_f32_e32 v48, s10, v236
	v_fmac_f32_e32 v50, s10, v236
	v_add_f32_e32 v26, v27, v26
	v_fmac_f32_e32 v44, s10, v236
	v_fmac_f32_e32 v46, s10, v236
	v_mul_f32_e32 v27, v50, v50
	v_mul_f32_e32 v30, v48, v48
	v_fmac_f32_e32 v27, v46, v46
	v_fmac_f32_e32 v30, v44, v44
	v_add_f32_e32 v27, v27, v30
	v_add_f32_e32 v26, v27, v26
	v_mov_b32_e32 v27, v2
	v_mov_b32_e32 v47, v50
	v_add_f32_dpp v26, v26, v26 quad_perm:[1,0,3,2] row_mask:0xf bank_mask:0xf bound_ctrl:1
	v_mov_b32_e32 v45, v48
	s_nop 0
	v_add_f32_dpp v26, v26, v26 quad_perm:[2,3,0,1] row_mask:0xf bank_mask:0xf bound_ctrl:1
	s_nop 1
	v_add_f32_dpp v26, v26, v26 row_half_mirror row_mask:0xf bank_mask:0xf bound_ctrl:1
	s_nop 1
	v_add_f32_dpp v26, v26, v26 row_mirror row_mask:0xf bank_mask:0xf bound_ctrl:1
	s_nop 1
	v_mov_b32_dpp v27, v26 row_bcast:15 row_mask:0xa bank_mask:0xf
	v_add_f32_e32 v26, v26, v27
	v_mov_b32_e32 v27, v2
	s_nop 1
	v_mov_b32_dpp v27, v26 row_bcast:31 row_mask:0xc bank_mask:0xf
	v_add_f32_e32 v26, v26, v27
	s_nop 0
	v_readlane_b32 s10, v26, 63
	s_nop 1
	v_fma_f32 v26, s10, v237, v252
	v_cmp_gt_f32_e32 vcc, s31, v26
	v_mul_f32_e32 v27, 0x4f800000, v26
	s_nop 0
	v_cndmask_b32_e32 v26, v26, v27, vcc
	v_sqrt_f32_e32 v27, v26
	s_nop 0
	v_add_u32_e32 v30, -1, v27
	v_fma_f32 v31, -v30, v27, v26
	v_cmp_ge_f32_e64 s[56:57], 0, v31
	v_add_u32_e32 v31, 1, v27
	s_nop 0
	v_cndmask_b32_e64 v30, v27, v30, s[56:57]
	v_fma_f32 v27, -v31, v27, v26
	v_cmp_lt_f32_e64 s[56:57], 0, v27
	s_nop 1
	v_cndmask_b32_e64 v27, v30, v31, s[56:57]
	v_mul_f32_e32 v30, 0x37800000, v27
	v_cndmask_b32_e32 v27, v27, v30, vcc
	v_cmp_class_f32_e32 vcc, v26, v234
	s_nop 1
	v_cndmask_b32_e32 v26, v27, v26, vcc
	v_div_scale_f32 v27, s[10:11], v26, v26, 1.0
	v_rcp_f32_e32 v30, v27
	s_mov_b64 s[10:11], -1
	v_fma_f32 v31, -v27, v30, 1.0
	v_fmac_f32_e32 v30, v31, v30
	v_div_scale_f32 v31, vcc, 1.0, v26, 1.0
	v_mul_f32_e32 v32, v31, v30
	v_fma_f32 v33, -v27, v32, v31
	v_fmac_f32_e32 v32, v33, v30
	v_fma_f32 v27, -v27, v32, v31
	v_div_fmas_f32 v27, v27, v30, v32
	v_mov_b64_e32 v[30:31], v[108:109]
	v_mov_b64_e32 v[32:33], v[110:111]
	v_mov_b64_e32 v[34:35], v[104:105]
	v_mov_b64_e32 v[36:37], v[106:107]
	v_mov_b64_e32 v[38:39], v[124:125]
	v_mov_b64_e32 v[40:41], v[126:127]
	v_mov_b64_e32 v[82:83], v[120:121]
	v_mov_b64_e32 v[84:85], v[122:123]
	v_div_fixup_f32 v80, v27, v26, 1.0
	v_mov_b32_e32 v27, v20
	v_mov_b32_e32 v20, v25
	v_mov_b32_e32 v26, v24
	v_pk_mul_f32 v[20:21], v[20:21], v[80:81] op_sel_hi:[1,0]
	v_pk_mul_f32 v[42:43], v[26:27], v[80:81] op_sel_hi:[1,0]
	v_pk_mul_f32 v[78:79], v[78:79], v[80:81] op_sel_hi:[1,0]
	v_pk_mul_f32 v[76:77], v[76:77], v[80:81] op_sel_hi:[1,0]
	s_and_b64 vcc, exec, s[54:55]
	s_nop 0
	v_pk_fma_f32 v[26:27], v[36:37], v[20:21], v[84:85]
	v_mov_b32_e32 v20, v28
	v_mov_b32_e32 v21, v22
	v_mov_b32_e32 v22, v29
	v_pk_mul_f32 v[20:21], v[20:21], v[80:81] op_sel_hi:[1,0]
	v_pk_mul_f32 v[22:23], v[22:23], v[80:81] op_sel_hi:[1,0]
	v_pk_fma_f32 v[24:25], v[34:35], v[42:43], v[82:83]
	v_pk_fma_f32 v[22:23], v[32:33], v[22:23], v[40:41]
	v_pk_fma_f32 v[20:21], v[30:31], v[20:21], v[38:39]
	v_mov_b64_e32 v[32:33], v[116:117]
	v_mov_b64_e32 v[34:35], v[118:119]
	v_mov_b64_e32 v[28:29], v[112:113]
	v_mov_b64_e32 v[30:31], v[114:115]
	v_mov_b64_e32 v[36:37], v[132:133]
	v_mov_b64_e32 v[38:39], v[134:135]
	v_mov_b64_e32 v[40:41], v[128:129]
	v_mov_b64_e32 v[42:43], v[130:131]
	s_nop 0
	v_pk_fma_f32 v[30:31], v[30:31], v[76:77], v[42:43]
	v_pk_fma_f32 v[28:29], v[28:29], v[78:79], v[40:41]
	v_pk_mul_f32 v[40:41], v[46:47], v[80:81] op_sel_hi:[1,0]
	v_pk_mul_f32 v[42:43], v[44:45], v[80:81] op_sel_hi:[1,0]
	v_pk_fma_f32 v[32:33], v[32:33], v[40:41], v[36:37]
	v_pk_fma_f32 v[34:35], v[34:35], v[42:43], v[38:39]
	s_cbranch_vccnz .LBB0_1706
; #define LAS __attribute__((address_space(3)))
; __device__ __forceinline__ float wave_sum(float v) { return rdlane(dpp_sum63(v), 63); }
; __device__ __forceinline__ void row_finalize(CArgs& A, Frame& F, int m, const f32x4 (&v)[4], int Ln) {
;     row_store_bf(WSP(bf16, WS_X) + (size_t)m * D, F.lane, v);
;     const LAS float* wig = (const LAS float*)(F.lds + WIG_OFF); const float* b_in = A.in[10] + (size_t)Ln * DIN + 3072;
;     float r[8];
; #pragma unroll
;     for (int c = 0; c < 8; ++c) { float s = 0.f;
; #pragma unroll
;         for (int j = 0; j < 4; ++j) { const f32x4 w = *(const LAS f32x4*)(wig + c * 1024 + RCOL(F.lane, j)); s += (v[j][0] * w[0] + v[j][1] * w[1]) + (v[j][2] * w[2] + v[j][3] * w[3]); }
;         r[c] = wave_sum(s); if (c & 1) asm volatile("" ::: "memory"); }
; __global__ void __launch_bounds__(NT, 2) fwd(const Args args) {
;     ...
;                     else {
; #pragma unroll
;                         for (int j = 0; j < 4; ++j) *(f32x4*)(F.out + O_Y + (size_t)(m + q) * D + RCOL(F.lane, j)) = v[j]; } } }
	v_lshl_add_u64 v[36:37], s[16:17], 0, v[54:55]
	s_mov_b64 s[10:11], 0
	global_store_dwordx4 v[36:37], v[24:27], off
	global_store_dwordx4 v[36:37], v[20:23], off offset:16
	global_store_dwordx4 v[36:37], v[28:31], off offset:2048
	global_store_dwordx4 v[36:37], v[32:35], off offset:2064
.LBB0_1706:
	s_andn2_b64 vcc, exec, s[10:11]
	s_cbranch_vccnz .LBB0_1710
	v_lshl_add_u64 v[238:239], s[58:59], 0, v[72:73]
	s_mov_b64 s[10:11], 0x7680000
	v_cvt_pk_bf16_f32 v240, v24, v25
	v_cvt_pk_bf16_f32 v241, v26, v27
	v_cvt_pk_bf16_f32 v242, v20, v21
	v_cvt_pk_bf16_f32 v243, v22, v23
	v_lshl_add_u64 v[238:239], v[238:239], 0, s[10:11]
	v_cvt_pk_bf16_f32 v244, v28, v29
	v_cvt_pk_bf16_f32 v245, v30, v31
	v_cvt_pk_bf16_f32 v246, v32, v33
	v_cvt_pk_bf16_f32 v247, v34, v35
	global_store_dwordx4 v[238:239], v[240:243], off
	global_store_dwordx4 v[238:239], v[244:247], off offset:1024
	v_lshl_add_u64 v[196:197], s[58:59], 0, v[74:75]
	s_waitcnt lgkmcnt(8)
	v_mul_f32_e32 v249, v25, v173
	v_mul_f32_e32 v250, v27, v175
	v_fmac_f32_e32 v249, v24, v172
	v_fmac_f32_e32 v250, v26, v174
	v_add_f32_e32 v249, v249, v250
	v_add_f32_e32 v227, 0, v249
	v_mul_f32_e32 v249, v21, v177
	v_mul_f32_e32 v250, v23, v179
	v_fmac_f32_e32 v249, v20, v176
	v_fmac_f32_e32 v250, v22, v178
	v_add_f32_e32 v249, v249, v250
	v_add_f32_e32 v227, v227, v249
	v_mul_f32_e32 v249, v29, v181
	v_mul_f32_e32 v250, v31, v183
	v_fmac_f32_e32 v249, v28, v180
	v_fmac_f32_e32 v250, v30, v182
	v_add_f32_e32 v249, v249, v250
	v_add_f32_e32 v227, v227, v249
	v_mul_f32_e32 v249, v33, v185
	v_mul_f32_e32 v250, v35, v187
	v_fmac_f32_e32 v249, v32, v184
	v_fmac_f32_e32 v250, v34, v186
	v_add_f32_e32 v249, v249, v250
	v_add_f32_e32 v227, v227, v249
	ds_read_b128 v[172:175], v94 offset:12288
	ds_read_b128 v[176:179], v94 offset:12304
	ds_read_b128 v[180:183], v94 offset:14336
	ds_read_b128 v[184:187], v94 offset:14352
	s_waitcnt lgkmcnt(8)
	v_mul_f32_e32 v249, v25, v203
	v_mul_f32_e32 v250, v27, v205
	v_fmac_f32_e32 v249, v24, v202
	v_fmac_f32_e32 v250, v26, v204
	v_add_f32_e32 v249, v249, v250
	v_add_f32_e32 v228, 0, v249
	v_mul_f32_e32 v249, v21, v207
	v_mul_f32_e32 v250, v23, v209
	v_fmac_f32_e32 v249, v20, v206
	v_fmac_f32_e32 v250, v22, v208
	v_add_f32_e32 v249, v249, v250
	v_add_f32_e32 v228, v228, v249
	v_mul_f32_e32 v249, v29, v211
	v_mul_f32_e32 v250, v31, v213
	v_fmac_f32_e32 v249, v28, v210
	v_fmac_f32_e32 v250, v30, v212
	v_add_f32_e32 v249, v249, v250
	v_add_f32_e32 v228, v228, v249
	v_mul_f32_e32 v249, v33, v215
	v_mul_f32_e32 v250, v35, v217
	v_fmac_f32_e32 v249, v32, v214
	v_fmac_f32_e32 v250, v34, v216
	v_add_f32_e32 v249, v249, v250
	v_add_f32_e32 v228, v228, v249
	ds_read_b128 v[202:205], v94 offset:16384
	ds_read_b128 v[206:209], v94 offset:16400
	ds_read_b128 v[210:213], v94 offset:18432
	ds_read_b128 v[214:217], v94 offset:18448
	s_waitcnt lgkmcnt(8)
	v_mul_f32_e32 v249, v25, v219
	v_mul_f32_e32 v250, v27, v221
	v_fmac_f32_e32 v249, v24, v218
	v_fmac_f32_e32 v250, v26, v220
	v_add_f32_e32 v249, v249, v250
	v_add_f32_e32 v229, 0, v249
	v_mul_f32_e32 v249, v21, v223
	v_mul_f32_e32 v250, v23, v225
	v_fmac_f32_e32 v249, v20, v222
	v_fmac_f32_e32 v250, v22, v224
	v_add_f32_e32 v249, v249, v250
	v_add_f32_e32 v229, v229, v249
	v_mul_f32_e32 v249, v29, v189
	v_mul_f32_e32 v250, v31, v191
	v_fmac_f32_e32 v249, v28, v188
	v_fmac_f32_e32 v250, v30, v190
	v_add_f32_e32 v249, v249, v250
	v_add_f32_e32 v229, v229, v249
	v_mul_f32_e32 v249, v33, v193
	v_mul_f32_e32 v250, v35, v195
	v_fmac_f32_e32 v249, v32, v192
	v_fmac_f32_e32 v250, v34, v194
	v_add_f32_e32 v249, v249, v250
	v_add_f32_e32 v229, v229, v249
	ds_read_b128 v[218:221], v94 offset:20480
	ds_read_b128 v[222:225], v94 offset:20496
	ds_read_b128 v[188:191], v94 offset:22528
	ds_read_b128 v[192:195], v94 offset:22544
	s_waitcnt lgkmcnt(8)
	v_mul_f32_e32 v249, v25, v173
	v_mul_f32_e32 v250, v27, v175
	v_fmac_f32_e32 v249, v24, v172
	v_fmac_f32_e32 v250, v26, v174
	v_add_f32_e32 v249, v249, v250
	v_add_f32_e32 v230, 0, v249
	v_mul_f32_e32 v249, v21, v177
	v_mul_f32_e32 v250, v23, v179
	v_fmac_f32_e32 v249, v20, v176
	v_fmac_f32_e32 v250, v22, v178
	v_add_f32_e32 v249, v249, v250
	v_add_f32_e32 v230, v230, v249
	v_mul_f32_e32 v249, v29, v181
	v_mul_f32_e32 v250, v31, v183
	v_fmac_f32_e32 v249, v28, v180
	v_fmac_f32_e32 v250, v30, v182
	v_add_f32_e32 v249, v249, v250
	v_add_f32_e32 v230, v230, v249
	v_mul_f32_e32 v249, v33, v185
	v_mul_f32_e32 v250, v35, v187
	v_fmac_f32_e32 v249, v32, v184
	v_fmac_f32_e32 v250, v34, v186
	v_add_f32_e32 v249, v249, v250
	v_add_f32_e32 v230, v230, v249
	ds_read_b128 v[172:175], v94 offset:24576
	ds_read_b128 v[176:179], v94 offset:24592
	ds_read_b128 v[180:183], v94 offset:26624
	ds_read_b128 v[184:187], v94 offset:26640
	s_waitcnt lgkmcnt(8)
	v_mul_f32_e32 v249, v25, v203
	v_mul_f32_e32 v250, v27, v205
	v_fmac_f32_e32 v249, v24, v202
	v_fmac_f32_e32 v250, v26, v204
	v_add_f32_e32 v249, v249, v250
	v_add_f32_e32 v231, 0, v249
	v_mul_f32_e32 v249, v21, v207
	v_mul_f32_e32 v250, v23, v209
	v_fmac_f32_e32 v249, v20, v206
	v_fmac_f32_e32 v250, v22, v208
	v_add_f32_e32 v249, v249, v250
	v_add_f32_e32 v231, v231, v249
	v_mul_f32_e32 v249, v29, v211
	v_mul_f32_e32 v250, v31, v213
	v_fmac_f32_e32 v249, v28, v210
	v_fmac_f32_e32 v250, v30, v212
	v_add_f32_e32 v249, v249, v250
	v_add_f32_e32 v231, v231, v249
	v_mul_f32_e32 v249, v33, v215
	v_mul_f32_e32 v250, v35, v217
	v_fmac_f32_e32 v249, v32, v214
	v_fmac_f32_e32 v250, v34, v216
	v_add_f32_e32 v249, v249, v250
	v_add_f32_e32 v231, v231, v249
	ds_read_b128 v[202:205], v94 offset:28672
	ds_read_b128 v[206:209], v94 offset:28688
	ds_read_b128 v[210:213], v94 offset:30720
	ds_read_b128 v[214:217], v94 offset:30736
	s_waitcnt lgkmcnt(8)
; #define LAS __attribute__((address_space(3)))
; __device__ __forceinline__ float wave_sum(float v) { return rdlane(dpp_sum63(v), 63); }
; __device__ __forceinline__ void row_finalize(CArgs& A, Frame& F, int m, const f32x4 (&v)[4], int Ln) {
;     ...
;     for (int c = 0; c < 8; ++c) { float s = 0.f;
; #pragma unroll
;         for (int j = 0; j < 4; ++j) { const f32x4 w = *(const LAS f32x4*)(wig + c * 1024 + RCOL(F.lane, j)); s += (v[j][0] * w[0] + v[j][1] * w[1]) + (v[j][2] * w[2] + v[j][3] * w[3]); }
;         r[c] = wave_sum(s); if (c & 1) asm volatile("" ::: "memory"); }
;     if (F.lane < 8) { float x = r[0];
; #pragma unroll
;         for (int c = 1; c < 8; ++c) x = (F.lane == c) ? r[c] : x;
;         WSP(float, WS_IGFG)[(size_t)m * 8 + F.lane] = x + b_in[F.lane]; }
	v_mul_f32_e32 v249, v25, v219
	v_mul_f32_e32 v250, v27, v221
	v_fmac_f32_e32 v249, v24, v218
	v_fmac_f32_e32 v250, v26, v220
	v_add_f32_e32 v249, v249, v250
	v_add_f32_e32 v232, 0, v249
	v_mul_f32_e32 v249, v21, v223
	v_mul_f32_e32 v250, v23, v225
	v_fmac_f32_e32 v249, v20, v222
	v_fmac_f32_e32 v250, v22, v224
	v_add_f32_e32 v249, v249, v250
	v_add_f32_e32 v232, v232, v249
	v_mul_f32_e32 v249, v29, v189
	v_mul_f32_e32 v250, v31, v191
	v_fmac_f32_e32 v249, v28, v188
	v_fmac_f32_e32 v250, v30, v190
	v_add_f32_e32 v249, v249, v250
	v_add_f32_e32 v232, v232, v249
	v_mul_f32_e32 v249, v33, v193
	v_mul_f32_e32 v250, v35, v195
	v_fmac_f32_e32 v249, v32, v192
	v_fmac_f32_e32 v250, v34, v194
	v_add_f32_e32 v249, v249, v250
	v_add_f32_e32 v232, v232, v249
	s_waitcnt lgkmcnt(4)
	v_mul_f32_e32 v249, v25, v173
	v_mul_f32_e32 v250, v27, v175
	v_fmac_f32_e32 v249, v24, v172
	v_fmac_f32_e32 v250, v26, v174
	v_add_f32_e32 v249, v249, v250
	v_add_f32_e32 v233, 0, v249
	v_mul_f32_e32 v249, v21, v177
	v_mul_f32_e32 v250, v23, v179
	v_fmac_f32_e32 v249, v20, v176
	v_fmac_f32_e32 v250, v22, v178
	v_add_f32_e32 v249, v249, v250
	v_add_f32_e32 v233, v233, v249
	v_mul_f32_e32 v249, v29, v181
	v_mul_f32_e32 v250, v31, v183
	v_fmac_f32_e32 v249, v28, v180
	v_fmac_f32_e32 v250, v30, v182
	v_add_f32_e32 v249, v249, v250
	v_add_f32_e32 v233, v233, v249
	v_mul_f32_e32 v249, v33, v185
	v_mul_f32_e32 v250, v35, v187
	v_fmac_f32_e32 v249, v32, v184
	v_fmac_f32_e32 v250, v34, v186
	v_add_f32_e32 v249, v249, v250
	v_add_f32_e32 v233, v233, v249
	s_waitcnt lgkmcnt(0)
	v_mul_f32_e32 v249, v25, v203
	v_mul_f32_e32 v250, v27, v205
	v_fmac_f32_e32 v249, v24, v202
	v_fmac_f32_e32 v250, v26, v204
	v_add_f32_e32 v249, v249, v250
	v_add_f32_e32 v248, 0, v249
	v_mul_f32_e32 v249, v21, v207
	v_mul_f32_e32 v250, v23, v209
	v_fmac_f32_e32 v249, v20, v206
	v_fmac_f32_e32 v250, v22, v208
	v_add_f32_e32 v249, v249, v250
	v_add_f32_e32 v248, v248, v249
	v_mul_f32_e32 v249, v29, v211
	v_mul_f32_e32 v250, v31, v213
	v_fmac_f32_e32 v249, v28, v210
	v_fmac_f32_e32 v250, v30, v212
	v_add_f32_e32 v249, v249, v250
	v_add_f32_e32 v248, v248, v249
	v_mul_f32_e32 v249, v33, v215
	v_mul_f32_e32 v250, v35, v217
	v_fmac_f32_e32 v249, v32, v214
	v_fmac_f32_e32 v250, v34, v216
	v_add_f32_e32 v249, v249, v250
	v_add_f32_e32 v248, v248, v249
	v_add_f32_dpp v227, v227, v227 quad_perm:[1,0,3,2] row_mask:0xf bank_mask:0xf bound_ctrl:1
	v_add_f32_dpp v228, v228, v228 quad_perm:[1,0,3,2] row_mask:0xf bank_mask:0xf bound_ctrl:1
	v_add_f32_dpp v229, v229, v229 quad_perm:[1,0,3,2] row_mask:0xf bank_mask:0xf bound_ctrl:1
	v_add_f32_dpp v230, v230, v230 quad_perm:[1,0,3,2] row_mask:0xf bank_mask:0xf bound_ctrl:1
	v_add_f32_dpp v231, v231, v231 quad_perm:[1,0,3,2] row_mask:0xf bank_mask:0xf bound_ctrl:1
	v_add_f32_dpp v232, v232, v232 quad_perm:[1,0,3,2] row_mask:0xf bank_mask:0xf bound_ctrl:1
	v_add_f32_dpp v233, v233, v233 quad_perm:[1,0,3,2] row_mask:0xf bank_mask:0xf bound_ctrl:1
	v_add_f32_dpp v248, v248, v248 quad_perm:[1,0,3,2] row_mask:0xf bank_mask:0xf bound_ctrl:1
	v_add_f32_dpp v227, v227, v227 quad_perm:[2,3,0,1] row_mask:0xf bank_mask:0xf bound_ctrl:1
	v_add_f32_dpp v228, v228, v228 quad_perm:[2,3,0,1] row_mask:0xf bank_mask:0xf bound_ctrl:1
	v_add_f32_dpp v229, v229, v229 quad_perm:[2,3,0,1] row_mask:0xf bank_mask:0xf bound_ctrl:1
	v_add_f32_dpp v230, v230, v230 quad_perm:[2,3,0,1] row_mask:0xf bank_mask:0xf bound_ctrl:1
	v_add_f32_dpp v231, v231, v231 quad_perm:[2,3,0,1] row_mask:0xf bank_mask:0xf bound_ctrl:1
	v_add_f32_dpp v232, v232, v232 quad_perm:[2,3,0,1] row_mask:0xf bank_mask:0xf bound_ctrl:1
	v_add_f32_dpp v233, v233, v233 quad_perm:[2,3,0,1] row_mask:0xf bank_mask:0xf bound_ctrl:1
	v_add_f32_dpp v248, v248, v248 quad_perm:[2,3,0,1] row_mask:0xf bank_mask:0xf bound_ctrl:1
	v_add_f32_dpp v227, v227, v227 row_half_mirror row_mask:0xf bank_mask:0xf bound_ctrl:1
	v_add_f32_dpp v228, v228, v228 row_half_mirror row_mask:0xf bank_mask:0xf bound_ctrl:1
	v_add_f32_dpp v229, v229, v229 row_half_mirror row_mask:0xf bank_mask:0xf bound_ctrl:1
	v_add_f32_dpp v230, v230, v230 row_half_mirror row_mask:0xf bank_mask:0xf bound_ctrl:1
	v_add_f32_dpp v231, v231, v231 row_half_mirror row_mask:0xf bank_mask:0xf bound_ctrl:1
	v_add_f32_dpp v232, v232, v232 row_half_mirror row_mask:0xf bank_mask:0xf bound_ctrl:1
	v_add_f32_dpp v233, v233, v233 row_half_mirror row_mask:0xf bank_mask:0xf bound_ctrl:1
	v_add_f32_dpp v248, v248, v248 row_half_mirror row_mask:0xf bank_mask:0xf bound_ctrl:1
	v_add_f32_dpp v227, v227, v227 row_mirror row_mask:0xf bank_mask:0xf bound_ctrl:1
	v_add_f32_dpp v228, v228, v228 row_mirror row_mask:0xf bank_mask:0xf bound_ctrl:1
	v_add_f32_dpp v229, v229, v229 row_mirror row_mask:0xf bank_mask:0xf bound_ctrl:1
	v_add_f32_dpp v230, v230, v230 row_mirror row_mask:0xf bank_mask:0xf bound_ctrl:1
	v_add_f32_dpp v231, v231, v231 row_mirror row_mask:0xf bank_mask:0xf bound_ctrl:1
	v_add_f32_dpp v232, v232, v232 row_mirror row_mask:0xf bank_mask:0xf bound_ctrl:1
	v_add_f32_dpp v233, v233, v233 row_mirror row_mask:0xf bank_mask:0xf bound_ctrl:1
	v_add_f32_dpp v248, v248, v248 row_mirror row_mask:0xf bank_mask:0xf bound_ctrl:1
	v_add_f32_dpp v227, v227, v227 row_bcast:15 row_mask:0xa bank_mask:0xf
	v_add_f32_dpp v228, v228, v228 row_bcast:15 row_mask:0xa bank_mask:0xf
	v_add_f32_dpp v229, v229, v229 row_bcast:15 row_mask:0xa bank_mask:0xf
	v_add_f32_dpp v230, v230, v230 row_bcast:15 row_mask:0xa bank_mask:0xf
	v_add_f32_dpp v231, v231, v231 row_bcast:15 row_mask:0xa bank_mask:0xf
	v_add_f32_dpp v232, v232, v232 row_bcast:15 row_mask:0xa bank_mask:0xf
	v_add_f32_dpp v233, v233, v233 row_bcast:15 row_mask:0xa bank_mask:0xf
	v_add_f32_dpp v248, v248, v248 row_bcast:15 row_mask:0xa bank_mask:0xf
	v_add_f32_dpp v227, v227, v227 row_bcast:31 row_mask:0xc bank_mask:0xf
	v_add_f32_dpp v228, v228, v228 row_bcast:31 row_mask:0xc bank_mask:0xf
	v_add_f32_dpp v229, v229, v229 row_bcast:31 row_mask:0xc bank_mask:0xf
	v_add_f32_dpp v230, v230, v230 row_bcast:31 row_mask:0xc bank_mask:0xf
	v_add_f32_dpp v231, v231, v231 row_bcast:31 row_mask:0xc bank_mask:0xf
	v_add_f32_dpp v232, v232, v232 row_bcast:31 row_mask:0xc bank_mask:0xf
	v_add_f32_dpp v233, v233, v233 row_bcast:31 row_mask:0xc bank_mask:0xf
	v_add_f32_dpp v248, v248, v248 row_bcast:31 row_mask:0xc bank_mask:0xf
	v_readlane_b32 s28, v227, 63
	v_readlane_b32 s29, v228, 63
	v_readlane_b32 s36, v229, 63
	v_readlane_b32 s37, v230, 63
	v_readlane_b32 s56, v231, 63
	v_readlane_b32 s57, v232, 63
	v_readlane_b32 s60, v233, 63
	v_readlane_b32 s61, v248, 63
	v_writelane_b32 v251, s28, 0
	v_writelane_b32 v251, s29, 1
	v_writelane_b32 v251, s36, 2
	v_writelane_b32 v251, s37, 3
	v_writelane_b32 v251, s56, 4
	v_writelane_b32 v251, s57, 5
	v_writelane_b32 v251, s60, 6
	v_writelane_b32 v251, s61, 7
	s_and_saveexec_b64 s[10:11], s[38:39]
	v_add_f32_e32 v251, v251, v168
	global_store_dword v[196:197], v251, off

; __device__ __forceinline__ float wave_sum(float v) { return rdlane(dpp_sum63(v), 63); }
; __device__ __forceinline__ void row_ln(f32x4 (&v)[4], const float* g, const float* b, int lane) {
;     float s = 0.f;
; #pragma unroll
;     for (int j = 0; j < 4; ++j) s += (v[j][0] + v[j][1]) + (v[j][2] + v[j][3]);
;     const float mean = wave_sum(s) * (1.f / D); float s2 = 0.f;
; #pragma unroll
;     for (int j = 0; j < 4; ++j) { v[j] = v[j] - mean; s2 += (v[j][0] * v[j][0] + v[j][1] * v[j][1]) + (v[j][2] * v[j][2] + v[j][3] * v[j][3]); }
;     const float rstd = 1.0f / sqrtf(wave_sum(s2) * (1.f / D) + LN_EPS);
; #pragma unroll
;     for (int j = 0; j < 4; ++j) { const f32x4 gg = *(const f32x4*)(g + RCOL(lane, j)), bb = *(const f32x4*)(b + RCOL(lane, j)); v[j] = v[j] * rstd * gg + bb; }
; }
; __global__ void __launch_bounds__(NT, 2) fwd(const Args args) {
;     ...
;                 for (int q = 0; q < 4; ++q) if (m + q < m1) { f32x4 v[4]; row_unpack(r[q], v); row_ln(v, g, bb, F.lane);
;                     if (L + 1 < DEPTH) row_finalize(A, F, m + q, v, L + 1);
.LBB0_1710:
	s_cmp_ge_i32 s27, s8
	s_cbranch_scc1 .LBB0_1717
	ds_read_b128 v[172:175], v94 offset:0
	ds_read_b128 v[176:179], v94 offset:16
	ds_read_b128 v[180:183], v94 offset:2048
	ds_read_b128 v[184:187], v94 offset:2064
	ds_read_b128 v[202:205], v94 offset:4096
	ds_read_b128 v[206:209], v94 offset:4112
	ds_read_b128 v[210:213], v94 offset:6144
	ds_read_b128 v[214:217], v94 offset:6160
	ds_read_b128 v[218:221], v94 offset:8192
	ds_read_b128 v[222:225], v94 offset:8208
	ds_read_b128 v[188:191], v94 offset:10240
	ds_read_b128 v[192:195], v94 offset:10256
	v_lshlrev_b32_e32 v46, 16, v16
	v_and_b32_e32 v47, 0xffff0000, v16
	v_lshlrev_b32_e32 v44, 16, v17
	v_and_b32_e32 v45, 0xffff0000, v17
	v_lshlrev_b32_e32 v17, 16, v13
	v_lshlrev_b32_e32 v16, 16, v12
	v_and_b32_e32 v13, 0xffff0000, v13
	v_and_b32_e32 v12, 0xffff0000, v12
	v_lshlrev_b32_e32 v38, 16, v18
	v_and_b32_e32 v42, 0xffff0000, v18
	v_lshlrev_b32_e32 v36, 16, v19
	v_and_b32_e32 v40, 0xffff0000, v19
	v_pk_add_f32 v[18:19], v[16:17], v[12:13]
	v_lshlrev_b32_e32 v21, 16, v15
	v_add_f32_e32 v18, v18, v19
	v_lshlrev_b32_e32 v20, 16, v14
	v_and_b32_e32 v15, 0xffff0000, v15
	v_and_b32_e32 v14, 0xffff0000, v14
	v_add_f32_e32 v41, 0, v18
	v_pk_add_f32 v[18:19], v[20:21], v[14:15]
	v_add_f32_e32 v39, v46, v47
	v_pk_add_f32 v[18:19], v[18:19], v[18:19] op_sel_hi:[0,1]
	v_add_f32_e32 v43, v44, v45
	v_mov_b32_e32 v37, v19
	v_pk_add_f32 v[22:23], v[38:39], v[42:43]
	v_pk_add_f32 v[18:19], v[36:37], v[40:41]
	s_nop 0
	v_pk_add_f32 v[18:19], v[22:23], v[18:19]
	s_nop 0
	v_add_f32_e32 v18, v18, v19
	v_mov_b32_e32 v19, v2
	s_nop 0
	v_add_f32_dpp v18, v18, v18 quad_perm:[1,0,3,2] row_mask:0xf bank_mask:0xf bound_ctrl:1
	s_nop 1
	v_add_f32_dpp v18, v18, v18 quad_perm:[2,3,0,1] row_mask:0xf bank_mask:0xf bound_ctrl:1
	s_nop 1
	v_add_f32_dpp v18, v18, v18 row_half_mirror row_mask:0xf bank_mask:0xf bound_ctrl:1
	s_nop 1
	v_add_f32_dpp v18, v18, v18 row_mirror row_mask:0xf bank_mask:0xf bound_ctrl:1
	s_nop 1
	v_mov_b32_dpp v19, v18 row_bcast:15 row_mask:0xa bank_mask:0xf
	v_add_f32_e32 v18, v18, v19
	v_mov_b32_e32 v19, v2
	s_nop 1
	v_mov_b32_dpp v19, v18 row_bcast:31 row_mask:0xc bank_mask:0xf
	v_add_f32_e32 v18, v18, v19
	s_nop 0
	v_readlane_b32 s10, v18, 63
	s_nop 1
	v_fmac_f32_e32 v13, s10, v236
	v_fmac_f32_e32 v12, s10, v236
	v_fmac_f32_e32 v17, s10, v236
	v_fmac_f32_e32 v16, s10, v236
	v_mul_f32_e32 v18, v12, v12
	v_mul_f32_e32 v19, v13, v13
	v_fmac_f32_e32 v18, v16, v16
	v_fmac_f32_e32 v19, v17, v17
	v_fmac_f32_e32 v15, s10, v236
	v_fmac_f32_e32 v14, s10, v236
	v_add_f32_e32 v18, v18, v19
	v_fmac_f32_e32 v21, s10, v236
	v_fmac_f32_e32 v20, s10, v236
	v_mul_f32_e32 v19, v14, v14
	v_mul_f32_e32 v22, v15, v15
	v_fmac_f32_e32 v19, v20, v20
	v_fmac_f32_e32 v22, v21, v21
	v_add_f32_e32 v19, v19, v22
	v_fmac_f32_e32 v45, s10, v236
	v_fmac_f32_e32 v47, s10, v236
	v_add_f32_e32 v18, v18, v19
	v_fmac_f32_e32 v44, s10, v236
	v_fmac_f32_e32 v46, s10, v236
	v_mul_f32_e32 v19, v47, v47
	v_mul_f32_e32 v22, v45, v45
	v_fmac_f32_e32 v19, v46, v46
	v_fmac_f32_e32 v22, v44, v44
	v_add_f32_e32 v19, v19, v22
	v_fmac_f32_e32 v40, s10, v236
	v_fmac_f32_e32 v42, s10, v236
	v_add_f32_e32 v18, v19, v18
	v_fmac_f32_e32 v36, s10, v236
	v_fmac_f32_e32 v38, s10, v236
	v_mul_f32_e32 v19, v42, v42
	v_mul_f32_e32 v22, v40, v40
	v_fmac_f32_e32 v19, v38, v38
	v_fmac_f32_e32 v22, v36, v36
	v_add_f32_e32 v19, v19, v22
	v_add_f32_e32 v18, v19, v18
	v_mov_b32_e32 v19, v2
	v_mov_b32_e32 v39, v42
	v_add_f32_dpp v18, v18, v18 quad_perm:[1,0,3,2] row_mask:0xf bank_mask:0xf bound_ctrl:1
	v_mov_b32_e32 v37, v40
	s_nop 0
	v_add_f32_dpp v18, v18, v18 quad_perm:[2,3,0,1] row_mask:0xf bank_mask:0xf bound_ctrl:1
	s_nop 1
	v_add_f32_dpp v18, v18, v18 row_half_mirror row_mask:0xf bank_mask:0xf bound_ctrl:1
	s_nop 1
	v_add_f32_dpp v18, v18, v18 row_mirror row_mask:0xf bank_mask:0xf bound_ctrl:1
	s_nop 1
	v_mov_b32_dpp v19, v18 row_bcast:15 row_mask:0xa bank_mask:0xf
	v_add_f32_e32 v18, v18, v19
	v_mov_b32_e32 v19, v2
	s_nop 1
	v_mov_b32_dpp v19, v18 row_bcast:31 row_mask:0xc bank_mask:0xf
	v_add_f32_e32 v18, v18, v19
	s_nop 0
	v_readlane_b32 s10, v18, 63
	s_nop 1
	v_fma_f32 v18, s10, v237, v252
	v_cmp_gt_f32_e32 vcc, s31, v18
	v_mul_f32_e32 v19, 0x4f800000, v18
	s_nop 0
	v_cndmask_b32_e32 v18, v18, v19, vcc
	v_sqrt_f32_e32 v19, v18
	s_nop 0
	v_add_u32_e32 v22, -1, v19
	v_fma_f32 v23, -v22, v19, v18
	v_cmp_ge_f32_e64 s[56:57], 0, v23
	v_add_u32_e32 v23, 1, v19
	s_nop 0
	v_cndmask_b32_e64 v22, v19, v22, s[56:57]
	v_fma_f32 v19, -v23, v19, v18
	v_cmp_lt_f32_e64 s[56:57], 0, v19
	s_nop 1
	v_cndmask_b32_e64 v19, v22, v23, s[56:57]
	v_mul_f32_e32 v22, 0x37800000, v19
	v_cndmask_b32_e32 v19, v19, v22, vcc
	v_cmp_class_f32_e32 vcc, v18, v234
	s_nop 1
	v_cndmask_b32_e32 v18, v19, v18, vcc
	v_div_scale_f32 v19, s[10:11], v18, v18, 1.0
	v_rcp_f32_e32 v22, v19
	s_mov_b64 s[10:11], -1
	v_fma_f32 v23, -v19, v22, 1.0
	v_fmac_f32_e32 v22, v23, v22
	v_div_scale_f32 v23, vcc, 1.0, v18, 1.0
	v_mul_f32_e32 v24, v23, v22
	v_fma_f32 v25, -v19, v24, v23
	v_fmac_f32_e32 v24, v25, v22
	v_fma_f32 v19, -v19, v24, v23
	v_div_fmas_f32 v19, v19, v22, v24
	v_mov_b64_e32 v[22:23], v[108:109]
	v_mov_b64_e32 v[24:25], v[110:111]
	v_mov_b64_e32 v[26:27], v[104:105]
	v_mov_b64_e32 v[28:29], v[106:107]
	v_mov_b64_e32 v[30:31], v[124:125]
	v_mov_b64_e32 v[32:33], v[126:127]
	v_mov_b64_e32 v[76:77], v[120:121]
	v_mov_b64_e32 v[78:79], v[122:123]
	v_div_fixup_f32 v48, v19, v18, 1.0
	v_mov_b32_e32 v19, v12
	v_mov_b32_e32 v12, v17
	v_mov_b32_e32 v18, v16
	v_pk_mul_f32 v[12:13], v[12:13], v[48:49] op_sel_hi:[1,0]
	v_pk_mul_f32 v[34:35], v[18:19], v[48:49] op_sel_hi:[1,0]
	v_pk_mul_f32 v[46:47], v[46:47], v[48:49] op_sel_hi:[1,0]
	v_pk_mul_f32 v[44:45], v[44:45], v[48:49] op_sel_hi:[1,0]
	s_and_b64 vcc, exec, s[54:55]
	s_nop 0
	v_pk_fma_f32 v[18:19], v[28:29], v[12:13], v[78:79]
	v_mov_b32_e32 v12, v20
	v_mov_b32_e32 v13, v14
	v_mov_b32_e32 v14, v21
	v_pk_mul_f32 v[12:13], v[12:13], v[48:49] op_sel_hi:[1,0]
	v_pk_mul_f32 v[14:15], v[14:15], v[48:49] op_sel_hi:[1,0]
	v_pk_fma_f32 v[16:17], v[26:27], v[34:35], v[76:77]
	v_pk_fma_f32 v[14:15], v[24:25], v[14:15], v[32:33]
	v_pk_fma_f32 v[12:13], v[22:23], v[12:13], v[30:31]
	v_mov_b64_e32 v[24:25], v[116:117]
	v_mov_b64_e32 v[26:27], v[118:119]
	v_mov_b64_e32 v[20:21], v[112:113]
	v_mov_b64_e32 v[22:23], v[114:115]
	v_mov_b64_e32 v[28:29], v[132:133]
	v_mov_b64_e32 v[30:31], v[134:135]
	v_mov_b64_e32 v[32:33], v[128:129]
	v_mov_b64_e32 v[34:35], v[130:131]
	s_nop 0
	v_pk_fma_f32 v[22:23], v[22:23], v[44:45], v[34:35]
	v_pk_fma_f32 v[20:21], v[20:21], v[46:47], v[32:33]
	v_pk_mul_f32 v[32:33], v[38:39], v[48:49] op_sel_hi:[1,0]
	v_pk_mul_f32 v[34:35], v[36:37], v[48:49] op_sel_hi:[1,0]
	v_pk_fma_f32 v[24:25], v[24:25], v[32:33], v[28:29]
	v_pk_fma_f32 v[26:27], v[26:27], v[34:35], v[30:31]
	s_cbranch_vccnz .LBB0_1713
; #define LAS __attribute__((address_space(3)))
; __device__ __forceinline__ float wave_sum(float v) { return rdlane(dpp_sum63(v), 63); }
; __device__ __forceinline__ void row_finalize(CArgs& A, Frame& F, int m, const f32x4 (&v)[4], int Ln) {
;     row_store_bf(WSP(bf16, WS_X) + (size_t)m * D, F.lane, v);
;     const LAS float* wig = (const LAS float*)(F.lds + WIG_OFF); const float* b_in = A.in[10] + (size_t)Ln * DIN + 3072;
;     float r[8];
; #pragma unroll
;     for (int c = 0; c < 8; ++c) { float s = 0.f;
; #pragma unroll
;         for (int j = 0; j < 4; ++j) { const f32x4 w = *(const LAS f32x4*)(wig + c * 1024 + RCOL(F.lane, j)); s += (v[j][0] * w[0] + v[j][1] * w[1]) + (v[j][2] * w[2] + v[j][3] * w[3]); }
;         r[c] = wave_sum(s); if (c & 1) asm volatile("" ::: "memory"); }
; __global__ void __launch_bounds__(NT, 2) fwd(const Args args) {
;     ...
;                     else {
; #pragma unroll
;                         for (int j = 0; j < 4; ++j) *(f32x4*)(F.out + O_Y + (size_t)(m + q) * D + RCOL(F.lane, j)) = v[j]; } } }
	v_lshl_add_u64 v[28:29], s[34:35], 0, v[54:55]
	s_mov_b64 s[10:11], 0
	global_store_dwordx4 v[28:29], v[16:19], off
	global_store_dwordx4 v[28:29], v[12:15], off offset:16
	global_store_dwordx4 v[28:29], v[20:23], off offset:2048
	global_store_dwordx4 v[28:29], v[24:27], off offset:2064
.LBB0_1713:
	s_andn2_b64 vcc, exec, s[10:11]
	s_cbranch_vccnz .LBB0_1717
	v_lshl_add_u64 v[238:239], s[58:59], 0, v[70:71]
	s_mov_b64 s[10:11], 0x7680000
	v_cvt_pk_bf16_f32 v240, v16, v17
	v_cvt_pk_bf16_f32 v241, v18, v19
	v_cvt_pk_bf16_f32 v242, v12, v13
	v_cvt_pk_bf16_f32 v243, v14, v15
	v_lshl_add_u64 v[238:239], v[238:239], 0, s[10:11]
	v_cvt_pk_bf16_f32 v244, v20, v21
	v_cvt_pk_bf16_f32 v245, v22, v23
	v_cvt_pk_bf16_f32 v246, v24, v25
	v_cvt_pk_bf16_f32 v247, v26, v27
	global_store_dwordx4 v[238:239], v[240:243], off
	global_store_dwordx4 v[238:239], v[244:247], off offset:1024
	v_lshl_add_u64 v[196:197], s[58:59], 0, v[68:69]
	s_waitcnt lgkmcnt(8)
	v_mul_f32_e32 v249, v17, v173
	v_mul_f32_e32 v250, v19, v175
	v_fmac_f32_e32 v249, v16, v172
	v_fmac_f32_e32 v250, v18, v174
	v_add_f32_e32 v249, v249, v250
	v_add_f32_e32 v227, 0, v249
	v_mul_f32_e32 v249, v13, v177
	v_mul_f32_e32 v250, v15, v179
	v_fmac_f32_e32 v249, v12, v176
	v_fmac_f32_e32 v250, v14, v178
	v_add_f32_e32 v249, v249, v250
	v_add_f32_e32 v227, v227, v249
	v_mul_f32_e32 v249, v21, v181
	v_mul_f32_e32 v250, v23, v183
	v_fmac_f32_e32 v249, v20, v180
	v_fmac_f32_e32 v250, v22, v182
	v_add_f32_e32 v249, v249, v250
	v_add_f32_e32 v227, v227, v249
	v_mul_f32_e32 v249, v25, v185
	v_mul_f32_e32 v250, v27, v187
	v_fmac_f32_e32 v249, v24, v184
	v_fmac_f32_e32 v250, v26, v186
	v_add_f32_e32 v249, v249, v250
	v_add_f32_e32 v227, v227, v249
	ds_read_b128 v[172:175], v94 offset:12288
	ds_read_b128 v[176:179], v94 offset:12304
	ds_read_b128 v[180:183], v94 offset:14336
	ds_read_b128 v[184:187], v94 offset:14352
	s_waitcnt lgkmcnt(8)
	v_mul_f32_e32 v249, v17, v203
	v_mul_f32_e32 v250, v19, v205
	v_fmac_f32_e32 v249, v16, v202
	v_fmac_f32_e32 v250, v18, v204
	v_add_f32_e32 v249, v249, v250
	v_add_f32_e32 v228, 0, v249
	v_mul_f32_e32 v249, v13, v207
	v_mul_f32_e32 v250, v15, v209
	v_fmac_f32_e32 v249, v12, v206
	v_fmac_f32_e32 v250, v14, v208
	v_add_f32_e32 v249, v249, v250
	v_add_f32_e32 v228, v228, v249
	v_mul_f32_e32 v249, v21, v211
	v_mul_f32_e32 v250, v23, v213
	v_fmac_f32_e32 v249, v20, v210
	v_fmac_f32_e32 v250, v22, v212
	v_add_f32_e32 v249, v249, v250
	v_add_f32_e32 v228, v228, v249
	v_mul_f32_e32 v249, v25, v215
	v_mul_f32_e32 v250, v27, v217
	v_fmac_f32_e32 v249, v24, v214
	v_fmac_f32_e32 v250, v26, v216
	v_add_f32_e32 v249, v249, v250
	v_add_f32_e32 v228, v228, v249
	ds_read_b128 v[202:205], v94 offset:16384
	ds_read_b128 v[206:209], v94 offset:16400
	ds_read_b128 v[210:213], v94 offset:18432
	ds_read_b128 v[214:217], v94 offset:18448
	s_waitcnt lgkmcnt(8)
	v_mul_f32_e32 v249, v17, v219
	v_mul_f32_e32 v250, v19, v221
	v_fmac_f32_e32 v249, v16, v218
	v_fmac_f32_e32 v250, v18, v220
	v_add_f32_e32 v249, v249, v250
	v_add_f32_e32 v229, 0, v249
	v_mul_f32_e32 v249, v13, v223
	v_mul_f32_e32 v250, v15, v225
	v_fmac_f32_e32 v249, v12, v222
	v_fmac_f32_e32 v250, v14, v224
	v_add_f32_e32 v249, v249, v250
	v_add_f32_e32 v229, v229, v249
	v_mul_f32_e32 v249, v21, v189
	v_mul_f32_e32 v250, v23, v191
	v_fmac_f32_e32 v249, v20, v188
	v_fmac_f32_e32 v250, v22, v190
	v_add_f32_e32 v249, v249, v250
	v_add_f32_e32 v229, v229, v249
	v_mul_f32_e32 v249, v25, v193
	v_mul_f32_e32 v250, v27, v195
	v_fmac_f32_e32 v249, v24, v192
	v_fmac_f32_e32 v250, v26, v194
	v_add_f32_e32 v249, v249, v250
	v_add_f32_e32 v229, v229, v249
	ds_read_b128 v[218:221], v94 offset:20480
	ds_read_b128 v[222:225], v94 offset:20496
	ds_read_b128 v[188:191], v94 offset:22528
	ds_read_b128 v[192:195], v94 offset:22544
	s_waitcnt lgkmcnt(8)
	v_mul_f32_e32 v249, v17, v173
	v_mul_f32_e32 v250, v19, v175
	v_fmac_f32_e32 v249, v16, v172
	v_fmac_f32_e32 v250, v18, v174
	v_add_f32_e32 v249, v249, v250
	v_add_f32_e32 v230, 0, v249
	v_mul_f32_e32 v249, v13, v177
	v_mul_f32_e32 v250, v15, v179
	v_fmac_f32_e32 v249, v12, v176
	v_fmac_f32_e32 v250, v14, v178
	v_add_f32_e32 v249, v249, v250
	v_add_f32_e32 v230, v230, v249
	v_mul_f32_e32 v249, v21, v181
	v_mul_f32_e32 v250, v23, v183
	v_fmac_f32_e32 v249, v20, v180
	v_fmac_f32_e32 v250, v22, v182
	v_add_f32_e32 v249, v249, v250
	v_add_f32_e32 v230, v230, v249
	v_mul_f32_e32 v249, v25, v185
	v_mul_f32_e32 v250, v27, v187
	v_fmac_f32_e32 v249, v24, v184
	v_fmac_f32_e32 v250, v26, v186
	v_add_f32_e32 v249, v249, v250
	v_add_f32_e32 v230, v230, v249
	ds_read_b128 v[172:175], v94 offset:24576
	ds_read_b128 v[176:179], v94 offset:24592
	ds_read_b128 v[180:183], v94 offset:26624
	ds_read_b128 v[184:187], v94 offset:26640
	s_waitcnt lgkmcnt(8)
	v_mul_f32_e32 v249, v17, v203
	v_mul_f32_e32 v250, v19, v205
	v_fmac_f32_e32 v249, v16, v202
	v_fmac_f32_e32 v250, v18, v204
	v_add_f32_e32 v249, v249, v250
	v_add_f32_e32 v231, 0, v249
	v_mul_f32_e32 v249, v13, v207
	v_mul_f32_e32 v250, v15, v209
	v_fmac_f32_e32 v249, v12, v206
	v_fmac_f32_e32 v250, v14, v208
	v_add_f32_e32 v249, v249, v250
	v_add_f32_e32 v231, v231, v249
	v_mul_f32_e32 v249, v21, v211
	v_mul_f32_e32 v250, v23, v213
	v_fmac_f32_e32 v249, v20, v210
	v_fmac_f32_e32 v250, v22, v212
	v_add_f32_e32 v249, v249, v250
	v_add_f32_e32 v231, v231, v249
	v_mul_f32_e32 v249, v25, v215
	v_mul_f32_e32 v250, v27, v217
	v_fmac_f32_e32 v249, v24, v214
	v_fmac_f32_e32 v250, v26, v216
	v_add_f32_e32 v249, v249, v250
	v_add_f32_e32 v231, v231, v249
	ds_read_b128 v[202:205], v94 offset:28672
	ds_read_b128 v[206:209], v94 offset:28688
	ds_read_b128 v[210:213], v94 offset:30720
	ds_read_b128 v[214:217], v94 offset:30736
	s_waitcnt lgkmcnt(8)
; #define LAS __attribute__((address_space(3)))
; __device__ __forceinline__ float wave_sum(float v) { return rdlane(dpp_sum63(v), 63); }
; __device__ __forceinline__ void row_finalize(CArgs& A, Frame& F, int m, const f32x4 (&v)[4], int Ln) {
;     ...
;     for (int c = 0; c < 8; ++c) { float s = 0.f;
; #pragma unroll
;         for (int j = 0; j < 4; ++j) { const f32x4 w = *(const LAS f32x4*)(wig + c * 1024 + RCOL(F.lane, j)); s += (v[j][0] * w[0] + v[j][1] * w[1]) + (v[j][2] * w[2] + v[j][3] * w[3]); }
;         r[c] = wave_sum(s); if (c & 1) asm volatile("" ::: "memory"); }
;     if (F.lane < 8) { float x = r[0];
; #pragma unroll
;         for (int c = 1; c < 8; ++c) x = (F.lane == c) ? r[c] : x;
;         WSP(float, WS_IGFG)[(size_t)m * 8 + F.lane] = x + b_in[F.lane]; }
	v_mul_f32_e32 v249, v17, v219
	v_mul_f32_e32 v250, v19, v221
	v_fmac_f32_e32 v249, v16, v218
	v_fmac_f32_e32 v250, v18, v220
	v_add_f32_e32 v249, v249, v250
	v_add_f32_e32 v232, 0, v249
	v_mul_f32_e32 v249, v13, v223
	v_mul_f32_e32 v250, v15, v225
	v_fmac_f32_e32 v249, v12, v222
	v_fmac_f32_e32 v250, v14, v224
	v_add_f32_e32 v249, v249, v250
	v_add_f32_e32 v232, v232, v249
	v_mul_f32_e32 v249, v21, v189
	v_mul_f32_e32 v250, v23, v191
	v_fmac_f32_e32 v249, v20, v188
	v_fmac_f32_e32 v250, v22, v190
	v_add_f32_e32 v249, v249, v250
	v_add_f32_e32 v232, v232, v249
	v_mul_f32_e32 v249, v25, v193
	v_mul_f32_e32 v250, v27, v195
	v_fmac_f32_e32 v249, v24, v192
	v_fmac_f32_e32 v250, v26, v194
	v_add_f32_e32 v249, v249, v250
	v_add_f32_e32 v232, v232, v249
	s_waitcnt lgkmcnt(4)
	v_mul_f32_e32 v249, v17, v173
	v_mul_f32_e32 v250, v19, v175
	v_fmac_f32_e32 v249, v16, v172
	v_fmac_f32_e32 v250, v18, v174
	v_add_f32_e32 v249, v249, v250
	v_add_f32_e32 v233, 0, v249
	v_mul_f32_e32 v249, v13, v177
	v_mul_f32_e32 v250, v15, v179
	v_fmac_f32_e32 v249, v12, v176
	v_fmac_f32_e32 v250, v14, v178
	v_add_f32_e32 v249, v249, v250
	v_add_f32_e32 v233, v233, v249
	v_mul_f32_e32 v249, v21, v181
	v_mul_f32_e32 v250, v23, v183
	v_fmac_f32_e32 v249, v20, v180
	v_fmac_f32_e32 v250, v22, v182
	v_add_f32_e32 v249, v249, v250
	v_add_f32_e32 v233, v233, v249
	v_mul_f32_e32 v249, v25, v185
	v_mul_f32_e32 v250, v27, v187
	v_fmac_f32_e32 v249, v24, v184
	v_fmac_f32_e32 v250, v26, v186
	v_add_f32_e32 v249, v249, v250
	v_add_f32_e32 v233, v233, v249
	s_waitcnt lgkmcnt(0)
	v_mul_f32_e32 v249, v17, v203
	v_mul_f32_e32 v250, v19, v205
	v_fmac_f32_e32 v249, v16, v202
	v_fmac_f32_e32 v250, v18, v204
	v_add_f32_e32 v249, v249, v250
	v_add_f32_e32 v248, 0, v249
	v_mul_f32_e32 v249, v13, v207
	v_mul_f32_e32 v250, v15, v209
	v_fmac_f32_e32 v249, v12, v206
	v_fmac_f32_e32 v250, v14, v208
	v_add_f32_e32 v249, v249, v250
	v_add_f32_e32 v248, v248, v249
	v_mul_f32_e32 v249, v21, v211
	v_mul_f32_e32 v250, v23, v213
	v_fmac_f32_e32 v249, v20, v210
	v_fmac_f32_e32 v250, v22, v212
	v_add_f32_e32 v249, v249, v250
	v_add_f32_e32 v248, v248, v249
	v_mul_f32_e32 v249, v25, v215
	v_mul_f32_e32 v250, v27, v217
	v_fmac_f32_e32 v249, v24, v214
	v_fmac_f32_e32 v250, v26, v216
	v_add_f32_e32 v249, v249, v250
	v_add_f32_e32 v248, v248, v249
	v_add_f32_dpp v227, v227, v227 quad_perm:[1,0,3,2] row_mask:0xf bank_mask:0xf bound_ctrl:1
	v_add_f32_dpp v228, v228, v228 quad_perm:[1,0,3,2] row_mask:0xf bank_mask:0xf bound_ctrl:1
	v_add_f32_dpp v229, v229, v229 quad_perm:[1,0,3,2] row_mask:0xf bank_mask:0xf bound_ctrl:1
	v_add_f32_dpp v230, v230, v230 quad_perm:[1,0,3,2] row_mask:0xf bank_mask:0xf bound_ctrl:1
	v_add_f32_dpp v231, v231, v231 quad_perm:[1,0,3,2] row_mask:0xf bank_mask:0xf bound_ctrl:1
	v_add_f32_dpp v232, v232, v232 quad_perm:[1,0,3,2] row_mask:0xf bank_mask:0xf bound_ctrl:1
	v_add_f32_dpp v233, v233, v233 quad_perm:[1,0,3,2] row_mask:0xf bank_mask:0xf bound_ctrl:1
	v_add_f32_dpp v248, v248, v248 quad_perm:[1,0,3,2] row_mask:0xf bank_mask:0xf bound_ctrl:1
	v_add_f32_dpp v227, v227, v227 quad_perm:[2,3,0,1] row_mask:0xf bank_mask:0xf bound_ctrl:1
	v_add_f32_dpp v228, v228, v228 quad_perm:[2,3,0,1] row_mask:0xf bank_mask:0xf bound_ctrl:1
	v_add_f32_dpp v229, v229, v229 quad_perm:[2,3,0,1] row_mask:0xf bank_mask:0xf bound_ctrl:1
	v_add_f32_dpp v230, v230, v230 quad_perm:[2,3,0,1] row_mask:0xf bank_mask:0xf bound_ctrl:1
	v_add_f32_dpp v231, v231, v231 quad_perm:[2,3,0,1] row_mask:0xf bank_mask:0xf bound_ctrl:1
	v_add_f32_dpp v232, v232, v232 quad_perm:[2,3,0,1] row_mask:0xf bank_mask:0xf bound_ctrl:1
	v_add_f32_dpp v233, v233, v233 quad_perm:[2,3,0,1] row_mask:0xf bank_mask:0xf bound_ctrl:1
	v_add_f32_dpp v248, v248, v248 quad_perm:[2,3,0,1] row_mask:0xf bank_mask:0xf bound_ctrl:1
	v_add_f32_dpp v227, v227, v227 row_half_mirror row_mask:0xf bank_mask:0xf bound_ctrl:1
	v_add_f32_dpp v228, v228, v228 row_half_mirror row_mask:0xf bank_mask:0xf bound_ctrl:1
	v_add_f32_dpp v229, v229, v229 row_half_mirror row_mask:0xf bank_mask:0xf bound_ctrl:1
	v_add_f32_dpp v230, v230, v230 row_half_mirror row_mask:0xf bank_mask:0xf bound_ctrl:1
	v_add_f32_dpp v231, v231, v231 row_half_mirror row_mask:0xf bank_mask:0xf bound_ctrl:1
	v_add_f32_dpp v232, v232, v232 row_half_mirror row_mask:0xf bank_mask:0xf bound_ctrl:1
	v_add_f32_dpp v233, v233, v233 row_half_mirror row_mask:0xf bank_mask:0xf bound_ctrl:1
	v_add_f32_dpp v248, v248, v248 row_half_mirror row_mask:0xf bank_mask:0xf bound_ctrl:1
	v_add_f32_dpp v227, v227, v227 row_mirror row_mask:0xf bank_mask:0xf bound_ctrl:1
	v_add_f32_dpp v228, v228, v228 row_mirror row_mask:0xf bank_mask:0xf bound_ctrl:1
	v_add_f32_dpp v229, v229, v229 row_mirror row_mask:0xf bank_mask:0xf bound_ctrl:1
	v_add_f32_dpp v230, v230, v230 row_mirror row_mask:0xf bank_mask:0xf bound_ctrl:1
	v_add_f32_dpp v231, v231, v231 row_mirror row_mask:0xf bank_mask:0xf bound_ctrl:1
	v_add_f32_dpp v232, v232, v232 row_mirror row_mask:0xf bank_mask:0xf bound_ctrl:1
	v_add_f32_dpp v233, v233, v233 row_mirror row_mask:0xf bank_mask:0xf bound_ctrl:1
	v_add_f32_dpp v248, v248, v248 row_mirror row_mask:0xf bank_mask:0xf bound_ctrl:1
	v_add_f32_dpp v227, v227, v227 row_bcast:15 row_mask:0xa bank_mask:0xf
	v_add_f32_dpp v228, v228, v228 row_bcast:15 row_mask:0xa bank_mask:0xf
	v_add_f32_dpp v229, v229, v229 row_bcast:15 row_mask:0xa bank_mask:0xf
	v_add_f32_dpp v230, v230, v230 row_bcast:15 row_mask:0xa bank_mask:0xf
	v_add_f32_dpp v231, v231, v231 row_bcast:15 row_mask:0xa bank_mask:0xf
	v_add_f32_dpp v232, v232, v232 row_bcast:15 row_mask:0xa bank_mask:0xf
	v_add_f32_dpp v233, v233, v233 row_bcast:15 row_mask:0xa bank_mask:0xf
	v_add_f32_dpp v248, v248, v248 row_bcast:15 row_mask:0xa bank_mask:0xf
	v_add_f32_dpp v227, v227, v227 row_bcast:31 row_mask:0xc bank_mask:0xf
	v_add_f32_dpp v228, v228, v228 row_bcast:31 row_mask:0xc bank_mask:0xf
	v_add_f32_dpp v229, v229, v229 row_bcast:31 row_mask:0xc bank_mask:0xf
	v_add_f32_dpp v230, v230, v230 row_bcast:31 row_mask:0xc bank_mask:0xf
	v_add_f32_dpp v231, v231, v231 row_bcast:31 row_mask:0xc bank_mask:0xf
	v_add_f32_dpp v232, v232, v232 row_bcast:31 row_mask:0xc bank_mask:0xf
	v_add_f32_dpp v233, v233, v233 row_bcast:31 row_mask:0xc bank_mask:0xf
	v_add_f32_dpp v248, v248, v248 row_bcast:31 row_mask:0xc bank_mask:0xf
	v_readlane_b32 s27, v227, 63
	v_readlane_b32 s28, v228, 63
	v_readlane_b32 s29, v229, 63
	v_readlane_b32 s36, v230, 63
	v_readlane_b32 s37, v231, 63
	v_readlane_b32 s56, v232, 63
	v_readlane_b32 s57, v233, 63
	v_readlane_b32 s60, v248, 63
	v_writelane_b32 v251, s27, 0
	v_writelane_b32 v251, s28, 1
	v_writelane_b32 v251, s29, 2
	v_writelane_b32 v251, s36, 3
	v_writelane_b32 v251, s37, 4
	v_writelane_b32 v251, s56, 5
	v_writelane_b32 v251, s57, 6
	v_writelane_b32 v251, s60, 7
	s_and_saveexec_b64 s[10:11], s[38:39]
	v_add_f32_e32 v251, v251, v168
	global_store_dword v[196:197], v251, off

; __device__ __forceinline__ float wave_sum(float v) { return rdlane(dpp_sum63(v), 63); }
; __device__ __forceinline__ void row_ln(f32x4 (&v)[4], const float* g, const float* b, int lane) {
;     float s = 0.f;
; #pragma unroll
;     for (int j = 0; j < 4; ++j) s += (v[j][0] + v[j][1]) + (v[j][2] + v[j][3]);
;     const float mean = wave_sum(s) * (1.f / D); float s2 = 0.f;
; #pragma unroll
;     for (int j = 0; j < 4; ++j) { v[j] = v[j] - mean; s2 += (v[j][0] * v[j][0] + v[j][1] * v[j][1]) + (v[j][2] * v[j][2] + v[j][3] * v[j][3]); }
;     const float rstd = 1.0f / sqrtf(wave_sum(s2) * (1.f / D) + LN_EPS);
; #pragma unroll
;     for (int j = 0; j < 4; ++j) { const f32x4 gg = *(const f32x4*)(g + RCOL(lane, j)), bb = *(const f32x4*)(b + RCOL(lane, j)); v[j] = v[j] * rstd * gg + bb; }
; }
; __global__ void __launch_bounds__(NT, 2) fwd(const Args args) {
;     ...
;                 for (int q = 0; q < 4; ++q) if (m + q < m1) { f32x4 v[4]; row_unpack(r[q], v); row_ln(v, g, bb, F.lane);
;                     if (L + 1 < DEPTH) row_finalize(A, F, m + q, v, L + 1);
;                     else {
; #pragma unroll
;                         for (int j = 0; j < 4; ++j) *(f32x4*)(F.out + O_Y + (size_t)(m + q) * D + RCOL(F.lane, j)) = v[j]; } } }
.LBB0_1717:
	s_cmp_ge_i32 s7, s8
	s_cbranch_scc1 .LBB0_1696
	ds_read_b128 v[172:175], v94 offset:0
	ds_read_b128 v[176:179], v94 offset:16
	ds_read_b128 v[180:183], v94 offset:2048
	ds_read_b128 v[184:187], v94 offset:2064
	ds_read_b128 v[202:205], v94 offset:4096
	ds_read_b128 v[206:209], v94 offset:4112
	ds_read_b128 v[210:213], v94 offset:6144
	ds_read_b128 v[214:217], v94 offset:6160
	ds_read_b128 v[218:221], v94 offset:8192
	ds_read_b128 v[222:225], v94 offset:8208
	ds_read_b128 v[188:191], v94 offset:10240
	ds_read_b128 v[192:195], v94 offset:10256
	v_lshlrev_b32_e32 v38, 16, v8
	v_and_b32_e32 v39, 0xffff0000, v8
	v_lshlrev_b32_e32 v36, 16, v9
	v_and_b32_e32 v37, 0xffff0000, v9
	v_lshlrev_b32_e32 v9, 16, v5
	v_lshlrev_b32_e32 v8, 16, v4
	v_and_b32_e32 v5, 0xffff0000, v5
	v_and_b32_e32 v4, 0xffff0000, v4
	v_lshlrev_b32_e32 v30, 16, v10
	v_and_b32_e32 v34, 0xffff0000, v10
	v_lshlrev_b32_e32 v28, 16, v11
	v_and_b32_e32 v32, 0xffff0000, v11
	v_pk_add_f32 v[10:11], v[8:9], v[4:5]
	v_lshlrev_b32_e32 v13, 16, v7
	v_add_f32_e32 v10, v10, v11
	v_lshlrev_b32_e32 v12, 16, v6
	v_and_b32_e32 v7, 0xffff0000, v7
	v_and_b32_e32 v6, 0xffff0000, v6
	v_add_f32_e32 v33, 0, v10
	v_pk_add_f32 v[10:11], v[12:13], v[6:7]
	v_add_f32_e32 v31, v38, v39
	v_pk_add_f32 v[10:11], v[10:11], v[10:11] op_sel_hi:[0,1]
	v_add_f32_e32 v35, v36, v37
	v_mov_b32_e32 v29, v11
	v_pk_add_f32 v[14:15], v[30:31], v[34:35]
	v_pk_add_f32 v[10:11], v[28:29], v[32:33]
	s_nop 0
	v_pk_add_f32 v[10:11], v[14:15], v[10:11]
	s_nop 0
	v_add_f32_e32 v10, v10, v11
	v_mov_b32_e32 v11, v2
	s_nop 0
	v_add_f32_dpp v10, v10, v10 quad_perm:[1,0,3,2] row_mask:0xf bank_mask:0xf bound_ctrl:1
	s_nop 1
	v_add_f32_dpp v10, v10, v10 quad_perm:[2,3,0,1] row_mask:0xf bank_mask:0xf bound_ctrl:1
	s_nop 1
	v_add_f32_dpp v10, v10, v10 row_half_mirror row_mask:0xf bank_mask:0xf bound_ctrl:1
	s_nop 1
	v_add_f32_dpp v10, v10, v10 row_mirror row_mask:0xf bank_mask:0xf bound_ctrl:1
	s_nop 1
	v_mov_b32_dpp v11, v10 row_bcast:15 row_mask:0xa bank_mask:0xf
	v_add_f32_e32 v10, v10, v11
	v_mov_b32_e32 v11, v2
	s_nop 1
	v_mov_b32_dpp v11, v10 row_bcast:31 row_mask:0xc bank_mask:0xf
	v_add_f32_e32 v10, v10, v11
	s_nop 0
	v_readlane_b32 s7, v10, 63
	s_nop 1
	v_fmac_f32_e32 v5, s7, v236
	v_fmac_f32_e32 v4, s7, v236
	v_fmac_f32_e32 v9, s7, v236
	v_fmac_f32_e32 v8, s7, v236
	v_mul_f32_e32 v10, v4, v4
	v_mul_f32_e32 v11, v5, v5
	v_fmac_f32_e32 v10, v8, v8
	v_fmac_f32_e32 v11, v9, v9
	v_fmac_f32_e32 v7, s7, v236
	v_fmac_f32_e32 v6, s7, v236
	v_add_f32_e32 v10, v10, v11
	v_fmac_f32_e32 v13, s7, v236
	v_fmac_f32_e32 v12, s7, v236
	v_mul_f32_e32 v11, v6, v6
	v_mul_f32_e32 v14, v7, v7
	v_fmac_f32_e32 v11, v12, v12
	v_fmac_f32_e32 v14, v13, v13
	v_add_f32_e32 v11, v11, v14
	v_fmac_f32_e32 v37, s7, v236
	v_fmac_f32_e32 v39, s7, v236
	v_add_f32_e32 v10, v10, v11
	v_fmac_f32_e32 v36, s7, v236
	v_fmac_f32_e32 v38, s7, v236
	v_mul_f32_e32 v11, v39, v39
	v_mul_f32_e32 v14, v37, v37
	v_fmac_f32_e32 v11, v38, v38
	v_fmac_f32_e32 v14, v36, v36
	v_add_f32_e32 v11, v11, v14
	v_fmac_f32_e32 v32, s7, v236
	v_fmac_f32_e32 v34, s7, v236
	v_add_f32_e32 v10, v11, v10
	v_fmac_f32_e32 v28, s7, v236
	v_fmac_f32_e32 v30, s7, v236
	v_mul_f32_e32 v11, v34, v34
	v_mul_f32_e32 v14, v32, v32
	v_fmac_f32_e32 v11, v30, v30
	v_fmac_f32_e32 v14, v28, v28
	v_add_f32_e32 v11, v11, v14
	v_add_f32_e32 v10, v11, v10
	v_mov_b32_e32 v11, v2
	v_mov_b32_e32 v31, v34
	v_add_f32_dpp v10, v10, v10 quad_perm:[1,0,3,2] row_mask:0xf bank_mask:0xf bound_ctrl:1
	v_mov_b32_e32 v29, v32
	s_nop 0
	v_add_f32_dpp v10, v10, v10 quad_perm:[2,3,0,1] row_mask:0xf bank_mask:0xf bound_ctrl:1
	s_nop 1
	v_add_f32_dpp v10, v10, v10 row_half_mirror row_mask:0xf bank_mask:0xf bound_ctrl:1
	s_nop 1
	v_add_f32_dpp v10, v10, v10 row_mirror row_mask:0xf bank_mask:0xf bound_ctrl:1
	s_nop 1
	v_mov_b32_dpp v11, v10 row_bcast:15 row_mask:0xa bank_mask:0xf
	v_add_f32_e32 v10, v10, v11
	v_mov_b32_e32 v11, v2
	s_nop 1
	v_mov_b32_dpp v11, v10 row_bcast:31 row_mask:0xc bank_mask:0xf
	v_add_f32_e32 v10, v10, v11
	s_nop 0
	v_readlane_b32 s7, v10, 63
	s_nop 1
	v_fma_f32 v10, s7, v237, v252
	v_cmp_gt_f32_e32 vcc, s31, v10
	v_mul_f32_e32 v11, 0x4f800000, v10
	s_nop 0
	v_cndmask_b32_e32 v10, v10, v11, vcc
	v_sqrt_f32_e32 v11, v10
	s_nop 0
	v_add_u32_e32 v14, -1, v11
	v_fma_f32 v15, -v14, v11, v10
	v_cmp_ge_f32_e64 s[56:57], 0, v15
	v_add_u32_e32 v15, 1, v11
	s_nop 0
	v_cndmask_b32_e64 v14, v11, v14, s[56:57]
	v_fma_f32 v11, -v15, v11, v10
	v_cmp_lt_f32_e64 s[56:57], 0, v11
	s_nop 1
	v_cndmask_b32_e64 v11, v14, v15, s[56:57]
	v_mul_f32_e32 v14, 0x37800000, v11
	v_cndmask_b32_e32 v11, v11, v14, vcc
	v_cmp_class_f32_e32 vcc, v10, v234
	s_nop 1
	v_cndmask_b32_e32 v10, v11, v10, vcc
	v_div_scale_f32 v11, s[10:11], v10, v10, 1.0
	v_rcp_f32_e32 v14, v11
	s_mov_b64 s[10:11], -1
	v_fma_f32 v15, -v11, v14, 1.0
	v_fmac_f32_e32 v14, v15, v14
	v_div_scale_f32 v15, vcc, 1.0, v10, 1.0
	v_mul_f32_e32 v16, v15, v14
	v_fma_f32 v17, -v11, v16, v15
	v_fmac_f32_e32 v16, v17, v14
	v_fma_f32 v11, -v11, v16, v15
	v_div_fmas_f32 v11, v11, v14, v16
	v_mov_b64_e32 v[14:15], v[108:109]
	v_mov_b64_e32 v[16:17], v[110:111]
	v_mov_b64_e32 v[18:19], v[104:105]
	v_mov_b64_e32 v[20:21], v[106:107]
	v_mov_b64_e32 v[22:23], v[124:125]
	v_mov_b64_e32 v[24:25], v[126:127]
	v_mov_b64_e32 v[42:43], v[120:121]
	v_mov_b64_e32 v[44:45], v[122:123]
	v_div_fixup_f32 v40, v11, v10, 1.0
	v_mov_b32_e32 v11, v4
	v_mov_b32_e32 v4, v9
	v_mov_b32_e32 v10, v8
	v_pk_mul_f32 v[4:5], v[4:5], v[40:41] op_sel_hi:[1,0]
	v_pk_mul_f32 v[26:27], v[10:11], v[40:41] op_sel_hi:[1,0]
	v_pk_mul_f32 v[38:39], v[38:39], v[40:41] op_sel_hi:[1,0]
	v_pk_mul_f32 v[36:37], v[36:37], v[40:41] op_sel_hi:[1,0]
	s_and_b64 vcc, exec, s[54:55]
	s_nop 0
	v_pk_fma_f32 v[10:11], v[20:21], v[4:5], v[44:45]
	v_mov_b32_e32 v4, v12
	v_mov_b32_e32 v5, v6
	v_mov_b32_e32 v6, v13
	v_pk_mul_f32 v[4:5], v[4:5], v[40:41] op_sel_hi:[1,0]
	v_pk_mul_f32 v[6:7], v[6:7], v[40:41] op_sel_hi:[1,0]
	v_pk_fma_f32 v[8:9], v[18:19], v[26:27], v[42:43]
	v_pk_fma_f32 v[6:7], v[16:17], v[6:7], v[24:25]
	v_pk_fma_f32 v[4:5], v[14:15], v[4:5], v[22:23]
	v_mov_b64_e32 v[16:17], v[116:117]
	v_mov_b64_e32 v[18:19], v[118:119]
	v_mov_b64_e32 v[12:13], v[112:113]
	v_mov_b64_e32 v[14:15], v[114:115]
	v_mov_b64_e32 v[20:21], v[132:133]
	v_mov_b64_e32 v[22:23], v[134:135]
	v_mov_b64_e32 v[24:25], v[128:129]
	v_mov_b64_e32 v[26:27], v[130:131]
	s_nop 0
	v_pk_fma_f32 v[14:15], v[14:15], v[36:37], v[26:27]
	v_pk_fma_f32 v[12:13], v[12:13], v[38:39], v[24:25]
	v_pk_mul_f32 v[24:25], v[30:31], v[40:41] op_sel_hi:[1,0]
	v_pk_mul_f32 v[26:27], v[28:29], v[40:41] op_sel_hi:[1,0]
	v_pk_fma_f32 v[16:17], v[16:17], v[24:25], v[20:21]
	v_pk_fma_f32 v[18:19], v[18:19], v[26:27], v[22:23]
	s_cbranch_vccnz .LBB0_1720
	v_lshl_add_u64 v[20:21], s[18:19], 0, v[54:55]
	s_mov_b64 s[10:11], 0
	global_store_dwordx4 v[20:21], v[8:11], off
	global_store_dwordx4 v[20:21], v[4:7], off offset:16
	global_store_dwordx4 v[20:21], v[12:15], off offset:2048
	global_store_dwordx4 v[20:21], v[16:19], off offset:2064
; #define LAS __attribute__((address_space(3)))
; __device__ __forceinline__ float wave_sum(float v) { return rdlane(dpp_sum63(v), 63); }
; __device__ __forceinline__ void row_finalize(CArgs& A, Frame& F, int m, const f32x4 (&v)[4], int Ln) {
;     row_store_bf(WSP(bf16, WS_X) + (size_t)m * D, F.lane, v);
;     const LAS float* wig = (const LAS float*)(F.lds + WIG_OFF); const float* b_in = A.in[10] + (size_t)Ln * DIN + 3072;
;     float r[8];
; #pragma unroll
;     for (int c = 0; c < 8; ++c) { float s = 0.f;
; #pragma unroll
;         for (int j = 0; j < 4; ++j) { const f32x4 w = *(const LAS f32x4*)(wig + c * 1024 + RCOL(F.lane, j)); s += (v[j][0] * w[0] + v[j][1] * w[1]) + (v[j][2] * w[2] + v[j][3] * w[3]); }
;         r[c] = wave_sum(s); if (c & 1) asm volatile("" ::: "memory"); }
.LBB0_1720:
	s_andn2_b64 vcc, exec, s[10:11]
	s_cbranch_vccnz .LBB0_1696
	v_lshl_add_u64 v[238:239], s[58:59], 0, v[66:67]
	s_mov_b64 s[10:11], 0x7680000
	v_cvt_pk_bf16_f32 v240, v8, v9
	v_cvt_pk_bf16_f32 v241, v10, v11
	v_cvt_pk_bf16_f32 v242, v4, v5
	v_cvt_pk_bf16_f32 v243, v6, v7
	v_lshl_add_u64 v[238:239], v[238:239], 0, s[10:11]
	v_cvt_pk_bf16_f32 v244, v12, v13
	v_cvt_pk_bf16_f32 v245, v14, v15
	v_cvt_pk_bf16_f32 v246, v16, v17
	v_cvt_pk_bf16_f32 v247, v18, v19
	global_store_dwordx4 v[238:239], v[240:243], off
	global_store_dwordx4 v[238:239], v[244:247], off offset:1024
	v_lshl_add_u64 v[196:197], s[58:59], 0, v[64:65]
	s_waitcnt lgkmcnt(8)
	v_mul_f32_e32 v249, v9, v173
	v_mul_f32_e32 v250, v11, v175
	v_fmac_f32_e32 v249, v8, v172
	v_fmac_f32_e32 v250, v10, v174
	v_add_f32_e32 v249, v249, v250
	v_add_f32_e32 v227, 0, v249
	v_mul_f32_e32 v249, v5, v177
	v_mul_f32_e32 v250, v7, v179
	v_fmac_f32_e32 v249, v4, v176
	v_fmac_f32_e32 v250, v6, v178
	v_add_f32_e32 v249, v249, v250
	v_add_f32_e32 v227, v227, v249
	v_mul_f32_e32 v249, v13, v181
	v_mul_f32_e32 v250, v15, v183
	v_fmac_f32_e32 v249, v12, v180
	v_fmac_f32_e32 v250, v14, v182
	v_add_f32_e32 v249, v249, v250
	v_add_f32_e32 v227, v227, v249
	v_mul_f32_e32 v249, v17, v185
	v_mul_f32_e32 v250, v19, v187
	v_fmac_f32_e32 v249, v16, v184
	v_fmac_f32_e32 v250, v18, v186
	v_add_f32_e32 v249, v249, v250
	v_add_f32_e32 v227, v227, v249
	ds_read_b128 v[172:175], v94 offset:12288
	ds_read_b128 v[176:179], v94 offset:12304
	ds_read_b128 v[180:183], v94 offset:14336
	ds_read_b128 v[184:187], v94 offset:14352
	s_waitcnt lgkmcnt(8)
	v_mul_f32_e32 v249, v9, v203
	v_mul_f32_e32 v250, v11, v205
	v_fmac_f32_e32 v249, v8, v202
	v_fmac_f32_e32 v250, v10, v204
	v_add_f32_e32 v249, v249, v250
	v_add_f32_e32 v228, 0, v249
	v_mul_f32_e32 v249, v5, v207
	v_mul_f32_e32 v250, v7, v209
	v_fmac_f32_e32 v249, v4, v206
	v_fmac_f32_e32 v250, v6, v208
	v_add_f32_e32 v249, v249, v250
	v_add_f32_e32 v228, v228, v249
	v_mul_f32_e32 v249, v13, v211
	v_mul_f32_e32 v250, v15, v213
	v_fmac_f32_e32 v249, v12, v210
	v_fmac_f32_e32 v250, v14, v212
	v_add_f32_e32 v249, v249, v250
	v_add_f32_e32 v228, v228, v249
	v_mul_f32_e32 v249, v17, v215
	v_mul_f32_e32 v250, v19, v217
	v_fmac_f32_e32 v249, v16, v214
	v_fmac_f32_e32 v250, v18, v216
	v_add_f32_e32 v249, v249, v250
	v_add_f32_e32 v228, v228, v249
	ds_read_b128 v[202:205], v94 offset:16384
	ds_read_b128 v[206:209], v94 offset:16400
	ds_read_b128 v[210:213], v94 offset:18432
	ds_read_b128 v[214:217], v94 offset:18448
	s_waitcnt lgkmcnt(8)
	v_mul_f32_e32 v249, v9, v219
	v_mul_f32_e32 v250, v11, v221
	v_fmac_f32_e32 v249, v8, v218
	v_fmac_f32_e32 v250, v10, v220
	v_add_f32_e32 v249, v249, v250
	v_add_f32_e32 v229, 0, v249
	v_mul_f32_e32 v249, v5, v223
	v_mul_f32_e32 v250, v7, v225
	v_fmac_f32_e32 v249, v4, v222
	v_fmac_f32_e32 v250, v6, v224
	v_add_f32_e32 v249, v249, v250
	v_add_f32_e32 v229, v229, v249
	v_mul_f32_e32 v249, v13, v189
	v_mul_f32_e32 v250, v15, v191
	v_fmac_f32_e32 v249, v12, v188
	v_fmac_f32_e32 v250, v14, v190
	v_add_f32_e32 v249, v249, v250
	v_add_f32_e32 v229, v229, v249
	v_mul_f32_e32 v249, v17, v193
	v_mul_f32_e32 v250, v19, v195
	v_fmac_f32_e32 v249, v16, v192
	v_fmac_f32_e32 v250, v18, v194
	v_add_f32_e32 v249, v249, v250
	v_add_f32_e32 v229, v229, v249
	ds_read_b128 v[218:221], v94 offset:20480
	ds_read_b128 v[222:225], v94 offset:20496
	ds_read_b128 v[188:191], v94 offset:22528
	ds_read_b128 v[192:195], v94 offset:22544
	s_waitcnt lgkmcnt(8)
	v_mul_f32_e32 v249, v9, v173
	v_mul_f32_e32 v250, v11, v175
	v_fmac_f32_e32 v249, v8, v172
	v_fmac_f32_e32 v250, v10, v174
	v_add_f32_e32 v249, v249, v250
	v_add_f32_e32 v230, 0, v249
	v_mul_f32_e32 v249, v5, v177
	v_mul_f32_e32 v250, v7, v179
	v_fmac_f32_e32 v249, v4, v176
	v_fmac_f32_e32 v250, v6, v178
	v_add_f32_e32 v249, v249, v250
	v_add_f32_e32 v230, v230, v249
	v_mul_f32_e32 v249, v13, v181
	v_mul_f32_e32 v250, v15, v183
	v_fmac_f32_e32 v249, v12, v180
	v_fmac_f32_e32 v250, v14, v182
	v_add_f32_e32 v249, v249, v250
	v_add_f32_e32 v230, v230, v249
	v_mul_f32_e32 v249, v17, v185
	v_mul_f32_e32 v250, v19, v187
	v_fmac_f32_e32 v249, v16, v184
	v_fmac_f32_e32 v250, v18, v186
	v_add_f32_e32 v249, v249, v250
	v_add_f32_e32 v230, v230, v249
	ds_read_b128 v[172:175], v94 offset:24576
	ds_read_b128 v[176:179], v94 offset:24592
	ds_read_b128 v[180:183], v94 offset:26624
	ds_read_b128 v[184:187], v94 offset:26640
	s_waitcnt lgkmcnt(8)
	v_mul_f32_e32 v249, v9, v203
	v_mul_f32_e32 v250, v11, v205
	v_fmac_f32_e32 v249, v8, v202
	v_fmac_f32_e32 v250, v10, v204
	v_add_f32_e32 v249, v249, v250
	v_add_f32_e32 v231, 0, v249
	v_mul_f32_e32 v249, v5, v207
	v_mul_f32_e32 v250, v7, v209
	v_fmac_f32_e32 v249, v4, v206
	v_fmac_f32_e32 v250, v6, v208
	v_add_f32_e32 v249, v249, v250
	v_add_f32_e32 v231, v231, v249
	v_mul_f32_e32 v249, v13, v211
	v_mul_f32_e32 v250, v15, v213
	v_fmac_f32_e32 v249, v12, v210
	v_fmac_f32_e32 v250, v14, v212
	v_add_f32_e32 v249, v249, v250
	v_add_f32_e32 v231, v231, v249
	v_mul_f32_e32 v249, v17, v215
	v_mul_f32_e32 v250, v19, v217
	v_fmac_f32_e32 v249, v16, v214
	v_fmac_f32_e32 v250, v18, v216
	v_add_f32_e32 v249, v249, v250
	v_add_f32_e32 v231, v231, v249
	ds_read_b128 v[202:205], v94 offset:28672
	ds_read_b128 v[206:209], v94 offset:28688
	ds_read_b128 v[210:213], v94 offset:30720
	ds_read_b128 v[214:217], v94 offset:30736
	s_waitcnt lgkmcnt(8)
; #define LAS __attribute__((address_space(3)))
; __device__ __forceinline__ float wave_sum(float v) { return rdlane(dpp_sum63(v), 63); }
; __device__ __forceinline__ void row_finalize(CArgs& A, Frame& F, int m, const f32x4 (&v)[4], int Ln) {
;     ...
;     for (int c = 0; c < 8; ++c) { float s = 0.f;
; #pragma unroll
;         for (int j = 0; j < 4; ++j) { const f32x4 w = *(const LAS f32x4*)(wig + c * 1024 + RCOL(F.lane, j)); s += (v[j][0] * w[0] + v[j][1] * w[1]) + (v[j][2] * w[2] + v[j][3] * w[3]); }
;         r[c] = wave_sum(s); if (c & 1) asm volatile("" ::: "memory"); }
;     if (F.lane < 8) { float x = r[0];
; #pragma unroll
;         for (int c = 1; c < 8; ++c) x = (F.lane == c) ? r[c] : x;
;         WSP(float, WS_IGFG)[(size_t)m * 8 + F.lane] = x + b_in[F.lane]; }
	v_mul_f32_e32 v249, v9, v219
	v_mul_f32_e32 v250, v11, v221
	v_fmac_f32_e32 v249, v8, v218
	v_fmac_f32_e32 v250, v10, v220
	v_add_f32_e32 v249, v249, v250
	v_add_f32_e32 v232, 0, v249
	v_mul_f32_e32 v249, v5, v223
	v_mul_f32_e32 v250, v7, v225
	v_fmac_f32_e32 v249, v4, v222
	v_fmac_f32_e32 v250, v6, v224
	v_add_f32_e32 v249, v249, v250
	v_add_f32_e32 v232, v232, v249
	v_mul_f32_e32 v249, v13, v189
	v_mul_f32_e32 v250, v15, v191
	v_fmac_f32_e32 v249, v12, v188
	v_fmac_f32_e32 v250, v14, v190
	v_add_f32_e32 v249, v249, v250
	v_add_f32_e32 v232, v232, v249
	v_mul_f32_e32 v249, v17, v193
	v_mul_f32_e32 v250, v19, v195
	v_fmac_f32_e32 v249, v16, v192
	v_fmac_f32_e32 v250, v18, v194
	v_add_f32_e32 v249, v249, v250
	v_add_f32_e32 v232, v232, v249
	s_waitcnt lgkmcnt(4)
	v_mul_f32_e32 v249, v9, v173
	v_mul_f32_e32 v250, v11, v175
	v_fmac_f32_e32 v249, v8, v172
	v_fmac_f32_e32 v250, v10, v174
	v_add_f32_e32 v249, v249, v250
	v_add_f32_e32 v233, 0, v249
	v_mul_f32_e32 v249, v5, v177
	v_mul_f32_e32 v250, v7, v179
	v_fmac_f32_e32 v249, v4, v176
	v_fmac_f32_e32 v250, v6, v178
	v_add_f32_e32 v249, v249, v250
	v_add_f32_e32 v233, v233, v249
	v_mul_f32_e32 v249, v13, v181
	v_mul_f32_e32 v250, v15, v183
	v_fmac_f32_e32 v249, v12, v180
	v_fmac_f32_e32 v250, v14, v182
	v_add_f32_e32 v249, v249, v250
	v_add_f32_e32 v233, v233, v249
	v_mul_f32_e32 v249, v17, v185
	v_mul_f32_e32 v250, v19, v187
	v_fmac_f32_e32 v249, v16, v184
	v_fmac_f32_e32 v250, v18, v186
	v_add_f32_e32 v249, v249, v250
	v_add_f32_e32 v233, v233, v249
	s_waitcnt lgkmcnt(0)
	v_mul_f32_e32 v249, v9, v203
	v_mul_f32_e32 v250, v11, v205
	v_fmac_f32_e32 v249, v8, v202
	v_fmac_f32_e32 v250, v10, v204
	v_add_f32_e32 v249, v249, v250
	v_add_f32_e32 v248, 0, v249
	v_mul_f32_e32 v249, v5, v207
	v_mul_f32_e32 v250, v7, v209
	v_fmac_f32_e32 v249, v4, v206
	v_fmac_f32_e32 v250, v6, v208
	v_add_f32_e32 v249, v249, v250
	v_add_f32_e32 v248, v248, v249
	v_mul_f32_e32 v249, v13, v211
	v_mul_f32_e32 v250, v15, v213
	v_fmac_f32_e32 v249, v12, v210
	v_fmac_f32_e32 v250, v14, v212
	v_add_f32_e32 v249, v249, v250
	v_add_f32_e32 v248, v248, v249
	v_mul_f32_e32 v249, v17, v215
	v_mul_f32_e32 v250, v19, v217
	v_fmac_f32_e32 v249, v16, v214
	v_fmac_f32_e32 v250, v18, v216
	v_add_f32_e32 v249, v249, v250
	v_add_f32_e32 v248, v248, v249
	v_add_f32_dpp v227, v227, v227 quad_perm:[1,0,3,2] row_mask:0xf bank_mask:0xf bound_ctrl:1
	v_add_f32_dpp v228, v228, v228 quad_perm:[1,0,3,2] row_mask:0xf bank_mask:0xf bound_ctrl:1
	v_add_f32_dpp v229, v229, v229 quad_perm:[1,0,3,2] row_mask:0xf bank_mask:0xf bound_ctrl:1
	v_add_f32_dpp v230, v230, v230 quad_perm:[1,0,3,2] row_mask:0xf bank_mask:0xf bound_ctrl:1
	v_add_f32_dpp v231, v231, v231 quad_perm:[1,0,3,2] row_mask:0xf bank_mask:0xf bound_ctrl:1
	v_add_f32_dpp v232, v232, v232 quad_perm:[1,0,3,2] row_mask:0xf bank_mask:0xf bound_ctrl:1
	v_add_f32_dpp v233, v233, v233 quad_perm:[1,0,3,2] row_mask:0xf bank_mask:0xf bound_ctrl:1
	v_add_f32_dpp v248, v248, v248 quad_perm:[1,0,3,2] row_mask:0xf bank_mask:0xf bound_ctrl:1
	v_add_f32_dpp v227, v227, v227 quad_perm:[2,3,0,1] row_mask:0xf bank_mask:0xf bound_ctrl:1
	v_add_f32_dpp v228, v228, v228 quad_perm:[2,3,0,1] row_mask:0xf bank_mask:0xf bound_ctrl:1
	v_add_f32_dpp v229, v229, v229 quad_perm:[2,3,0,1] row_mask:0xf bank_mask:0xf bound_ctrl:1
	v_add_f32_dpp v230, v230, v230 quad_perm:[2,3,0,1] row_mask:0xf bank_mask:0xf bound_ctrl:1
	v_add_f32_dpp v231, v231, v231 quad_perm:[2,3,0,1] row_mask:0xf bank_mask:0xf bound_ctrl:1
	v_add_f32_dpp v232, v232, v232 quad_perm:[2,3,0,1] row_mask:0xf bank_mask:0xf bound_ctrl:1
	v_add_f32_dpp v233, v233, v233 quad_perm:[2,3,0,1] row_mask:0xf bank_mask:0xf bound_ctrl:1
	v_add_f32_dpp v248, v248, v248 quad_perm:[2,3,0,1] row_mask:0xf bank_mask:0xf bound_ctrl:1
	v_add_f32_dpp v227, v227, v227 row_half_mirror row_mask:0xf bank_mask:0xf bound_ctrl:1
	v_add_f32_dpp v228, v228, v228 row_half_mirror row_mask:0xf bank_mask:0xf bound_ctrl:1
	v_add_f32_dpp v229, v229, v229 row_half_mirror row_mask:0xf bank_mask:0xf bound_ctrl:1
	v_add_f32_dpp v230, v230, v230 row_half_mirror row_mask:0xf bank_mask:0xf bound_ctrl:1
	v_add_f32_dpp v231, v231, v231 row_half_mirror row_mask:0xf bank_mask:0xf bound_ctrl:1
	v_add_f32_dpp v232, v232, v232 row_half_mirror row_mask:0xf bank_mask:0xf bound_ctrl:1
	v_add_f32_dpp v233, v233, v233 row_half_mirror row_mask:0xf bank_mask:0xf bound_ctrl:1
	v_add_f32_dpp v248, v248, v248 row_half_mirror row_mask:0xf bank_mask:0xf bound_ctrl:1
	v_add_f32_dpp v227, v227, v227 row_mirror row_mask:0xf bank_mask:0xf bound_ctrl:1
	v_add_f32_dpp v228, v228, v228 row_mirror row_mask:0xf bank_mask:0xf bound_ctrl:1
	v_add_f32_dpp v229, v229, v229 row_mirror row_mask:0xf bank_mask:0xf bound_ctrl:1
	v_add_f32_dpp v230, v230, v230 row_mirror row_mask:0xf bank_mask:0xf bound_ctrl:1
	v_add_f32_dpp v231, v231, v231 row_mirror row_mask:0xf bank_mask:0xf bound_ctrl:1
	v_add_f32_dpp v232, v232, v232 row_mirror row_mask:0xf bank_mask:0xf bound_ctrl:1
	v_add_f32_dpp v233, v233, v233 row_mirror row_mask:0xf bank_mask:0xf bound_ctrl:1
	v_add_f32_dpp v248, v248, v248 row_mirror row_mask:0xf bank_mask:0xf bound_ctrl:1
	v_add_f32_dpp v227, v227, v227 row_bcast:15 row_mask:0xa bank_mask:0xf
	v_add_f32_dpp v228, v228, v228 row_bcast:15 row_mask:0xa bank_mask:0xf
	v_add_f32_dpp v229, v229, v229 row_bcast:15 row_mask:0xa bank_mask:0xf
	v_add_f32_dpp v230, v230, v230 row_bcast:15 row_mask:0xa bank_mask:0xf
	v_add_f32_dpp v231, v231, v231 row_bcast:15 row_mask:0xa bank_mask:0xf
	v_add_f32_dpp v232, v232, v232 row_bcast:15 row_mask:0xa bank_mask:0xf
	v_add_f32_dpp v233, v233, v233 row_bcast:15 row_mask:0xa bank_mask:0xf
	v_add_f32_dpp v248, v248, v248 row_bcast:15 row_mask:0xa bank_mask:0xf
	v_add_f32_dpp v227, v227, v227 row_bcast:31 row_mask:0xc bank_mask:0xf
	v_add_f32_dpp v228, v228, v228 row_bcast:31 row_mask:0xc bank_mask:0xf
	v_add_f32_dpp v229, v229, v229 row_bcast:31 row_mask:0xc bank_mask:0xf
	v_add_f32_dpp v230, v230, v230 row_bcast:31 row_mask:0xc bank_mask:0xf
	v_add_f32_dpp v231, v231, v231 row_bcast:31 row_mask:0xc bank_mask:0xf
	v_add_f32_dpp v232, v232, v232 row_bcast:31 row_mask:0xc bank_mask:0xf
	v_add_f32_dpp v233, v233, v233 row_bcast:31 row_mask:0xc bank_mask:0xf
	v_add_f32_dpp v248, v248, v248 row_bcast:31 row_mask:0xc bank_mask:0xf
	v_readlane_b32 s7, v227, 63
	v_readlane_b32 s27, v228, 63
	v_readlane_b32 s28, v229, 63
	v_readlane_b32 s29, v230, 63
	v_readlane_b32 s36, v231, 63
	v_readlane_b32 s37, v232, 63
	v_readlane_b32 s54, v233, 63
	v_readlane_b32 s55, v248, 63
	v_writelane_b32 v251, s7, 0
	v_writelane_b32 v251, s27, 1
	v_writelane_b32 v251, s28, 2
	v_writelane_b32 v251, s29, 3
	v_writelane_b32 v251, s36, 4
	v_writelane_b32 v251, s37, 5
	v_writelane_b32 v251, s54, 6
	v_writelane_b32 v251, s55, 7
	s_and_saveexec_b64 s[10:11], s[38:39]
	v_add_f32_e32 v251, v251, v168
	global_store_dword v[196:197], v251, off
	s_branch .LBB0_1695
